# LN fast path + gate-GEMM epilogue rewritten (all loads up front, cross-lane stats sum) + ret-core Q waits no longer drain K/V prefetch
# speedup vs baseline: 1.0034x; 1.0034x over previous
.LBB0_49:
	s_and_b64 vcc, exec, s[42:43]
	s_cbranch_vccz .LBB0_226
	v_mov_b32_e32 v0, v135
	v_readlane_b32 s1, v252, 49
	v_readfirstlane_b32 s0, v0
	s_ashr_i32 s0, s0, 6
	s_add_i32 s6, s0, s1
	s_cmpk_gt_i32 s6, 0x7fff
	v_readlane_b32 s3, v252, 8
	s_cbranch_scc1 .LBB0_53
	s_mul_i32 s0, s16, 0x90000
	v_readlane_b32 s1, v252, 4
	s_add_u32 s7, s1, s0
	v_readlane_b32 s0, v252, 5
	s_addc_u32 s18, s0, 0
	s_cmp_eq_u32 s64, 1
	s_cselect_b64 s[0:1], -1, 0
	v_cndmask_b32_e64 v8, 0.5, 1.0, s[0:1]
	s_and_b64 s[0:1], s[0:1], s[92:93]
	s_and_b64 s[0:1], s[0:1], exec
	s_brev_b32 s0, 16
	s_cselect_b32 s0, s0, 0xc000000
	v_readlane_b32 s20, v252, 2
	v_readlane_b32 s21, v252, 3
	s_add_u32 s0, s20, s0
	s_addc_u32 s1, s21, 0
	s_cmp_lt_u32 s86, 39
	s_mul_i32 s30, s64, 0xc00
	s_cselect_b64 s[20:21], -1, 0
	s_add_i32 s25, s30, 0xc00
	s_cmp_eq_u32 s64, 2
	s_cselect_b64 s[22:23], -1, 0
	s_and_b64 s[34:35], s[22:23], exec
	s_cselect_b32 s34, 0, s25
	s_and_b64 s[20:21], s[22:23], s[20:21]
	s_and_b64 s[20:21], s[20:21], exec
	s_cselect_b32 s20, 0x90000, 0
	s_add_u32 s25, s7, s20
	s_addc_u32 s40, s18, 0
	s_lshl_b64 s[20:21], s[30:31], 2
	s_add_u32 s20, s7, s20
	s_mov_b32 s35, s31
	s_addc_u32 s21, s18, s21
	s_lshl_b64 s[22:23], s[34:35], 2
	s_add_u32 s22, s25, s22
	s_mul_i32 s7, s16, 3
	s_addc_u32 s23, s40, s23
	s_add_i32 s7, s64, s7
	v_lshlrev_b32_e32 v0, 2, v0
	s_lshl_b32 s30, s7, 10
	v_readlane_b32 s40, v254, 24
	v_and_b32_e32 v1, 0xfc, v0
	s_movk_i32 s7, 0x80
	v_bfrev_b32_e32 v2, 0.5
	s_lshl_b64 s[34:35], s[30:31], 2
	v_readlane_b32 s50, v254, 34
	s_waitcnt vmcnt(0)
	v_bitop3_b32 v52, v0, s7, v2 bitop3:0x6c
	v_lshlrev_b32_e32 v32, 2, v1
	v_lshlrev_b32_e32 v0, 1, v1
	v_mov_b32_e32 v1, v33
	v_readlane_b32 s41, v254, 25
	v_readlane_b32 s51, v254, 35
	s_add_u32 s40, s50, s34
	v_lshl_add_u64 v[18:19], s[0:1], 0, v[0:1]
	v_lshl_add_u64 v[2:3], s[20:21], 0, v[32:33]
	s_mov_b64 s[0:1], 0x2000
	v_readlane_b32 s48, v254, 32
	s_addc_u32 s41, s51, s35
	v_lshl_add_u64 v[20:21], v[2:3], 0, s[0:1]
	v_lshl_add_u64 v[22:23], s[22:23], 0, v[32:33]
	s_mov_b64 s[0:1], 0x1000
	v_readlane_b32 s49, v254, 33
	s_add_u32 s34, s48, s34
	v_lshl_add_u64 v[24:25], v[22:23], 0, s[0:1]
	v_readlane_b32 s0, v252, 6
	s_addc_u32 s35, s49, s35
	v_readlane_b32 s1, v252, 7
	v_mov_b32_e32 v10, v8
	v_mov_b32_e32 v11, v8
	v_lshl_add_u64 v[12:13], s[34:35], 0, v[32:33]
	v_lshl_add_u64 v[14:15], s[40:41], 0, v[32:33]
	v_lshl_add_u64 v[16:17], s[68:69], 0, v[32:33]
	v_lshl_add_u64 v[26:27], s[0:1], 0, v[0:1]
	v_readlane_b32 s42, v254, 26
	v_readlane_b32 s43, v254, 27
	v_readlane_b32 s44, v254, 28
	v_readlane_b32 s45, v254, 29
	v_readlane_b32 s46, v254, 30
	v_readlane_b32 s47, v254, 31
	v_readlane_b32 s52, v254, 36
	v_readlane_b32 s53, v254, 37
	v_readlane_b32 s54, v254, 38
	v_readlane_b32 s55, v254, 39
	s_cmpk_lg_i32 s3, 0x800
	s_cbranch_scc1 .LBB0_52
	v_mov_b32_e32 v96, v52
	s_lshr_b32 s0, s6, 7
	s_and_b32 s7, s6, 7
	s_andn2_b32 s6, s6, 7
	s_lshl_b32 s6, s6, 4
	s_or_b32 s6, s6, s7
	v_mad_i64_i32 v[28:29], s[22:23], s0, v193, v[20:21]
	v_mad_i64_i32 v[30:31], s[22:23], s0, v193, v[22:23]
	v_mad_i64_i32 v[0:1], s[22:23], s0, v193, v[24:25]
	global_load_dwordx4 v[194:197], v[28:29], off
	global_load_dwordx4 v[198:201], v[28:29], off offset:1024
	global_load_dwordx4 v[202:205], v[28:29], off offset:2048
	global_load_dwordx4 v[206:209], v[28:29], off offset:3072
	global_load_dwordx4 v[210:213], v[30:31], off
	global_load_dwordx4 v[214:217], v[30:31], off offset:1024
	global_load_dwordx4 v[218:221], v[30:31], off offset:2048
	global_load_dwordx4 v[222:225], v[30:31], off offset:3072
	global_load_dwordx4 v[226:229], v[0:1], off
	global_load_dwordx4 v[230:233], v[0:1], off offset:1024
	global_load_dwordx4 v[234:237], v[0:1], off offset:2048
	global_load_dwordx4 v[238:241], v[0:1], off offset:3072
	global_load_dwordx4 v[140:143], v[12:13], off
	global_load_dwordx4 v[144:147], v[12:13], off offset:1024
	global_load_dwordx4 v[148:151], v[12:13], off offset:2048
	global_load_dwordx4 v[152:155], v[12:13], off offset:3072
	global_load_dwordx4 v[98:101], v[14:15], off
	global_load_dwordx4 v[102:105], v[14:15], off offset:1024
	global_load_dwordx4 v[106:109], v[14:15], off offset:2048
	global_load_dwordx4 v[110:113], v[14:15], off offset:3072
	s_ashr_i32 s7, s6, 31
	s_lshl_b64 s[40:41], s[6:7], 12
	s_lshl_b64 s[20:21], s[6:7], 11
	v_lshl_add_u64 v[82:83], v[16:17], 0, s[40:41]
	v_lshl_add_u64 v[84:85], v[18:19], 0, s[20:21]
	v_lshl_add_u64 v[88:89], v[26:27], 0, s[20:21]
	v_lshl_add_u64 v[86:87], v[16:17], 0, s[40:41]
	s_mov_b64 s[0:1], 0x8000
	s_mov_b64 s[20:21], 0x4000
	global_load_dwordx4 v[34:37], v[82:83], off nt
	global_load_dwordx4 v[38:41], v[82:83], off offset:1024 nt
	global_load_dwordx4 v[42:45], v[82:83], off offset:2048 nt
	global_load_dwordx4 v[46:49], v[82:83], off offset:3072 nt
	global_load_dwordx2 v[50:51], v[84:85], off nt
	global_load_dwordx2 v[52:53], v[84:85], off offset:512 nt
	global_load_dwordx2 v[54:55], v[84:85], off offset:1024 nt
	global_load_dwordx2 v[56:57], v[84:85], off offset:1536 nt
	v_lshl_add_u64 v[82:83], v[82:83], 0, s[0:1]
	v_lshl_add_u64 v[84:85], v[84:85], 0, s[20:21]
	global_load_dwordx4 v[58:61], v[82:83], off nt
	global_load_dwordx4 v[62:65], v[82:83], off offset:1024 nt
	global_load_dwordx4 v[66:69], v[82:83], off offset:2048 nt
	global_load_dwordx4 v[70:73], v[82:83], off offset:3072 nt
	global_load_dwordx2 v[74:75], v[84:85], off nt
	global_load_dwordx2 v[76:77], v[84:85], off offset:512 nt
	global_load_dwordx2 v[78:79], v[84:85], off offset:1024 nt
	global_load_dwordx2 v[80:81], v[84:85], off offset:1536 nt
	v_lshl_add_u64 v[82:83], v[82:83], 0, s[0:1]
	v_lshl_add_u64 v[84:85], v[84:85], 0, s[20:21]
	s_waitcnt vmcnt(16)
	v_pk_add_f32 v[194:195], v[194:195], 1.0 op_sel_hi:[1,0]
	v_pk_add_f32 v[196:197], v[196:197], 1.0 op_sel_hi:[1,0]
	v_pk_add_f32 v[198:199], v[198:199], 1.0 op_sel_hi:[1,0]
	v_pk_add_f32 v[200:201], v[200:201], 1.0 op_sel_hi:[1,0]
	v_pk_add_f32 v[202:203], v[202:203], 1.0 op_sel_hi:[1,0]
	v_pk_add_f32 v[204:205], v[204:205], 1.0 op_sel_hi:[1,0]
	v_pk_add_f32 v[206:207], v[206:207], 1.0 op_sel_hi:[1,0]
	v_pk_add_f32 v[208:209], v[208:209], 1.0 op_sel_hi:[1,0]
	v_pk_add_f32 v[226:227], v[226:227], 1.0 op_sel_hi:[1,0]
	v_pk_add_f32 v[228:229], v[228:229], 1.0 op_sel_hi:[1,0]
	v_pk_add_f32 v[230:231], v[230:231], 1.0 op_sel_hi:[1,0]
	v_pk_add_f32 v[232:233], v[232:233], 1.0 op_sel_hi:[1,0]
	v_pk_add_f32 v[234:235], v[234:235], 1.0 op_sel_hi:[1,0]
	v_pk_add_f32 v[236:237], v[236:237], 1.0 op_sel_hi:[1,0]
	v_pk_add_f32 v[238:239], v[238:239], 1.0 op_sel_hi:[1,0]
	v_pk_add_f32 v[240:241], v[240:241], 1.0 op_sel_hi:[1,0]
	s_mov_b32 s6, 7
	s_waitcnt vmcnt(8)

.LBB0_203:
	v_mov_b32_e32 v168, v137
	s_waitcnt vmcnt(8)
	v_perm_b32 v109, v68, v72, s10
	v_ashrrev_i32_e32 v108, 5, v168
	v_lshlrev_b32_e32 v32, 4, v168
	v_and_b32_e32 v32, 0x1f0, v32
	v_mul_lo_u32 v34, v108, s38
	v_and_b32_e32 v151, 63, v168
	v_add3_u32 v34, 0, v32, v34
	v_ashrrev_i32_e32 v35, 3, v168
	v_lshlrev_b32_e32 v194, 2, v151
	ds_write_b128 v34, v[0:3]
	ds_write_b128 v34, v[4:7] offset:8448
	ds_write_b128 v34, v[8:11] offset:16896
	ds_write_b128 v34, v[12:15] offset:25344
	ds_write_b128 v34, v[16:19] offset:33792
	ds_write_b128 v34, v[20:23] offset:42240
	ds_write_b128 v34, v[48:51] offset:50688
	ds_write_b128 v34, v[64:67] offset:59136
	v_and_b32_e32 v34, -8, v35
	v_add_u32_e32 v110, s33, v194
	v_mad_u64_u32 v[112:113], s[0:1], v34, s83, v[110:111]
	v_perm_b32 v111, v68, v72, s11
	s_lshl_b32 s42, s35, 7
	ds_write2_b32 v112, v109, v111 offset1:68
	v_perm_b32 v109, v69, v73, s10
	v_perm_b32 v111, v69, v73, s11
	ds_write2_b32 v112, v109, v111 offset0:136 offset1:204
	v_perm_b32 v109, v70, v74, s10
	v_perm_b32 v111, v70, v74, s11
	v_add_u32_e32 v113, 0x400, v112
	s_or_b32 s42, s44, s42
	ds_write2_b32 v113, v109, v111 offset0:16 offset1:84
	v_perm_b32 v109, v71, v75, s10
	v_or_b32_e32 v35, 7, v35
	s_cmp_lg_u32 s35, 15
	ds_write_b32 v112, v109 offset:1632
	v_perm_b32 v109, v71, v75, s11
	v_mad_u64_u32 v[110:111], s[0:1], v35, s83, v[110:111]
	s_cselect_b64 s[56:57], -1, 0
	s_cmp_eq_u32 s35, 15
	s_mov_b32 s43, s45
	ds_write_b32 v110, v109
	s_add_u32 s0, s42, 0x80
	s_addc_u32 s1, s43, 0
	v_ashrrev_i32_e32 v109, 31, v108
	v_lshl_add_u64 v[0:1], s[0:1], 0, v[108:109]
	v_lshlrev_b64 v[0:1], 13, v[0:1]
	v_lshl_add_u64 v[0:1], s[48:49], 0, v[0:1]
	v_lshl_add_u64 v[48:49], v[0:1], 0, v[32:33]
	v_add_co_u32_e32 v4, vcc, s76, v48
	v_lshl_or_b32 v68, v151, 1, s0
	s_nop 0
	v_addc_co_u32_e32 v5, vcc, 0, v49, vcc
	v_add_co_u32_e32 v8, vcc, s77, v48
	v_mov_b32_e32 v69, s1
	s_nop 0
	v_addc_co_u32_e32 v9, vcc, 0, v49, vcc
	v_add_co_u32_e32 v12, vcc, s78, v48
	v_lshlrev_b64 v[68:69], 13, v[68:69]
	s_nop 0
	v_addc_co_u32_e32 v13, vcc, 0, v49, vcc
	v_add_co_u32_e32 v16, vcc, s79, v48
	v_lshl_add_u64 v[68:69], s[62:63], 0, v[68:69]
	s_nop 0
	v_addc_co_u32_e32 v17, vcc, 0, v49, vcc
	v_add_co_u32_e32 v20, vcc, s80, v48
	v_lshl_add_u64 v[68:69], v[68:69], 0, s[30:31]
	s_nop 0
	v_addc_co_u32_e32 v21, vcc, 0, v49, vcc
	v_add_co_u32_e32 v50, vcc, s81, v48
	s_mov_b32 s55, s31
	s_nop 0
	v_addc_co_u32_e32 v51, vcc, 0, v49, vcc
	v_add_co_u32_e32 v64, vcc, s82, v48
	v_lshl_add_u64 v[68:69], v[68:69], 0, s[54:55]
	v_ashrrev_i32_e32 v35, 31, v34
	v_addc_co_u32_e32 v65, vcc, 0, v49, vcc
	v_lshl_add_u64 v[34:35], v[34:35], 1, v[68:69]
	v_add_co_u32_e32 v68, vcc, 0x1000, v34
	global_load_dwordx4 v[0:3], v[48:49], off offset:2048
	s_nop 0
	global_load_dwordx4 v[4:7], v[4:5], off offset:2048
	v_addc_co_u32_e32 v69, vcc, 0, v35, vcc
	v_add_co_u32_e32 v34, vcc, 0x3000, v34
	global_load_dwordx4 v[8:11], v[8:9], off offset:2048
	s_nop 0
	global_load_dwordx4 v[12:15], v[12:13], off offset:2048
	s_nop 0
	global_load_dwordx4 v[16:19], v[16:17], off offset:2048
	s_nop 0
	global_load_dwordx4 v[20:23], v[20:21], off offset:2048
	s_nop 0
	global_load_dwordx4 v[48:51], v[50:51], off offset:2048
	s_nop 0
	global_load_dwordx4 v[64:67], v[64:65], off offset:2048
	v_addc_co_u32_e32 v35, vcc, 0, v35, vcc
	global_load_dwordx4 v[68:71], v[68:69], off
	s_nop 0
	global_load_dwordx4 v[72:75], v[34:35], off

.LBB0_207:
	v_add_u32_e32 v205, 0, v201
	ds_read_b128 v[124:127], v205
	ds_read_b128 v[206:209], v205 offset:64
	ds_read_b128 v[128:131], v205 offset:8448
	v_cmp_ge_i32_e32 vcc, v34, v204
	v_or_b32_e32 v213, 3, v204
	v_or_b32_e32 v214, 2, v204
	v_or_b32_e32 v212, 16, v204
	v_or_b32_e32 v211, 17, v204
	s_add_i32 s55, s55, -1
	s_waitcnt vmcnt(11) lgkmcnt(2)
	v_mfma_f32_16x16x32_bf16 v[124:127], v[124:127], v[40:43], 0
	v_add_u32_e32 v201, 0x4200, v201
	s_cmp_eq_u32 s55, 0
	s_waitcnt vmcnt(16) lgkmcnt(1)
	v_mfma_f32_16x16x32_bf16 v[124:127], v[206:209], v[24:27], v[124:127]
	ds_read_b128 v[206:209], v205 offset:8512
	s_waitcnt lgkmcnt(1)
	v_mfma_f32_16x16x32_bf16 v[128:131], v[128:131], v[40:43], 0
	s_waitcnt lgkmcnt(0)
	v_mfma_f32_16x16x32_bf16 v[128:131], v[206:209], v[24:27], v[128:131]
	ds_read_b128 v[206:209], v205 offset:128
	s_waitcnt vmcnt(15) lgkmcnt(0)
	v_mfma_f32_16x16x32_bf16 v[124:127], v[206:209], v[28:31], v[124:127]
	ds_read_b128 v[206:209], v205 offset:8576
	s_waitcnt lgkmcnt(0)
	v_mfma_f32_16x16x32_bf16 v[128:131], v[206:209], v[28:31], v[128:131]
	ds_read_b128 v[206:209], v205 offset:192
	s_waitcnt vmcnt(14) lgkmcnt(0)
	v_mfma_f32_16x16x32_bf16 v[124:127], v[206:209], v[36:39], v[124:127]
	ds_read_b128 v[206:209], v205 offset:8640
	s_waitcnt lgkmcnt(0)
	v_mfma_f32_16x16x32_bf16 v[128:131], v[206:209], v[36:39], v[128:131]
	ds_read_b128 v[206:209], v205 offset:256
	s_waitcnt vmcnt(13) lgkmcnt(0)
	v_mfma_f32_16x16x32_bf16 v[124:127], v[206:209], v[44:47], v[124:127]
	ds_read_b128 v[206:209], v205 offset:8704
	s_waitcnt lgkmcnt(0)
	v_mfma_f32_16x16x32_bf16 v[128:131], v[206:209], v[44:47], v[128:131]
	ds_read_b128 v[206:209], v205 offset:320
	s_waitcnt vmcnt(12) lgkmcnt(0)
	v_mfma_f32_16x16x32_bf16 v[124:127], v[206:209], v[52:55], v[124:127]
	ds_read_b128 v[206:209], v205 offset:8768
	s_waitcnt lgkmcnt(0)
	v_mfma_f32_16x16x32_bf16 v[128:131], v[206:209], v[52:55], v[128:131]
	ds_read_b128 v[206:209], v205 offset:384
	s_waitcnt vmcnt(11) lgkmcnt(0)
	v_mfma_f32_16x16x32_bf16 v[124:127], v[206:209], v[56:59], v[124:127]
	ds_read_b128 v[206:209], v205 offset:8832
	s_waitcnt lgkmcnt(0)
	v_mfma_f32_16x16x32_bf16 v[128:131], v[206:209], v[56:59], v[128:131]
	ds_read_b128 v[206:209], v205 offset:448
	s_waitcnt vmcnt(10) lgkmcnt(0)
	v_mfma_f32_16x16x32_bf16 v[206:209], v[206:209], v[60:63], v[124:127]
	s_nop 2
	ds_read_b128 v[124:127], v205 offset:8896
	s_waitcnt lgkmcnt(0)
	v_mfma_f32_16x16x32_bf16 v[124:127], v[124:127], v[60:63], v[128:131]
	s_nop 2
	v_cvt_f32_i32_e32 v129, v203
	v_add_u32_e32 v130, -1, v203
	v_cvt_f32_i32_e32 v130, v130
	v_mul_f32_e32 v128, 0x3d800000, v206
	v_mul_f32_e32 v129, v147, v129
	v_exp_f32_e32 v129, v129
	v_mul_f32_e32 v130, v147, v130
	v_exp_f32_e32 v130, v130
	v_pk_mul_f32 v[124:125], v[124:125], s[8:9] op_sel_hi:[1,0]
	v_mul_f32_e32 v128, v129, v128
	v_mul_f32_e32 v129, 0x3d800000, v207
	v_cndmask_b32_e32 v205, 0, v128, vcc
	v_cmp_gt_i32_e32 vcc, v34, v204
	v_mul_f32_e32 v129, v130, v129
	v_add_u32_e32 v128, -16, v203
	v_cndmask_b32_e32 v210, 0, v129, vcc
	v_subrev_u32_e32 v129, 17, v203
	v_cvt_f32_i32_e32 v128, v128
	v_cvt_f32_i32_e32 v129, v129
	v_pk_mul_f32 v[130:131], v[208:209], s[8:9] op_sel_hi:[1,0]
	v_pk_mul_f32 v[126:127], v[126:127], s[8:9] op_sel_hi:[1,0]
	v_mul_f32_e32 v128, v147, v128
	v_mul_f32_e32 v129, v147, v129
	v_exp_f32_e32 v128, v128
	v_exp_f32_e32 v129, v129
	v_cmp_ge_i32_e32 vcc, v34, v214
	v_or_b32_e32 v209, 18, v204
	v_or_b32_e32 v208, 19, v204
	v_pk_mul_f32 v[128:129], v[128:129], v[124:125]
	v_sub_u32_e32 v124, v34, v214
	v_sub_u32_e32 v125, v34, v213
	v_cvt_f32_i32_e32 v124, v124
	v_cvt_f32_i32_e32 v125, v125
	v_add_u32_e32 v204, 32, v204
	v_subrev_u32_e32 v203, 32, v203
	v_mul_f32_e32 v124, v147, v124
	v_mul_f32_e32 v125, v147, v125
	v_exp_f32_e32 v124, v124
	v_exp_f32_e32 v125, v125
	s_nop 0
	v_pk_mul_f32 v[130:131], v[124:125], v[130:131]
	v_sub_u32_e32 v124, v200, v214
	v_sub_u32_e32 v125, v200, v213
	v_cvt_f32_i32_e32 v124, v124
	v_cvt_f32_i32_e32 v125, v125
	v_mul_f32_e32 v124, v147, v124
	v_mul_f32_e32 v125, v147, v125
	v_exp_f32_e32 v124, v124
	v_exp_f32_e32 v125, v125
	s_nop 0
	v_pk_mul_f32 v[206:207], v[124:125], v[126:127]
	v_cvt_pk_bf16_f32 v125, v130, v131
	v_cndmask_b32_e32 v126, 0, v125, vcc
	v_lshrrev_b32_e32 v125, 16, v125
	v_cmp_ge_i32_e32 vcc, v35, v213
	v_cvt_pk_bf16_f32 v124, v205, v210
	v_add_u32_e32 v205, 0, v202
	v_cndmask_b32_e32 v125, 0, v125, vcc
	v_perm_b32 v125, v125, v126, s13
	v_cvt_pk_bf16_f32 v126, v128, v129
	v_cmp_ge_i32_e32 vcc, v34, v212
	v_add_u32_e32 v130, 0x19020, v205
	ds_read_b64 v[130:131], v130
	v_cndmask_b32_e32 v127, 0, v126, vcc
	v_lshrrev_b32_e32 v126, 16, v126
	v_cmp_ge_i32_e32 vcc, v35, v211
	v_add_u32_e32 v202, 64, v202
	s_nop 0
	v_cndmask_b32_e32 v126, 0, v126, vcc
	v_perm_b32 v126, v126, v127, s13
	v_cvt_pk_bf16_f32 v127, v206, v207
	v_cmp_ge_i32_e32 vcc, v34, v209
	s_nop 1
	v_cndmask_b32_e32 v128, 0, v127, vcc
	v_lshrrev_b32_e32 v127, 16, v127
	v_cmp_ge_i32_e32 vcc, v35, v208
	s_nop 1
	v_cndmask_b32_e32 v127, 0, v127, vcc
	v_perm_b32 v127, v127, v128, s13
	v_add_u32_e32 v128, 0x19000, v205
	ds_read_b64 v[128:129], v128
	s_waitcnt lgkmcnt(0)
	v_mfma_f32_16x16x32_bf16 v[120:123], v[128:131], v[124:127], v[120:123]
	v_add_u32_e32 v128, 0x1a100, v205
	v_add_u32_e32 v130, 0x1a120, v205
	ds_read_b64 v[128:129], v128
	ds_read_b64 v[130:131], v130
	s_waitcnt lgkmcnt(0)
	v_mfma_f32_16x16x32_bf16 v[116:119], v[128:131], v[124:127], v[116:119]
	v_add_u32_e32 v128, 0x1b200, v205
	v_add_u32_e32 v130, 0x1b220, v205
	ds_read_b64 v[128:129], v128
	ds_read_b64 v[130:131], v130
	s_waitcnt lgkmcnt(0)
	v_mfma_f32_16x16x32_bf16 v[112:115], v[128:131], v[124:127], v[112:115]
	v_add_u32_e32 v128, 0x1c300, v205
	v_add_u32_e32 v130, 0x1c320, v205
	ds_read_b64 v[128:129], v128
	ds_read_b64 v[130:131], v130
	s_waitcnt lgkmcnt(0)
	v_mfma_f32_16x16x32_bf16 v[108:111], v[128:131], v[124:127], v[108:111]
	s_cbranch_scc0 .LBB0_207
	s_mov_b64 s[60:61], 0

.LBB0_211:
	v_add_u32_e32 v35, 0, v195
	v_mad_u32_u24 v195, v164, s38, v35
	v_add_u32_e32 v124, 0x1d400, v195
	ds_read_b128 v[124:127], v124
	v_add_u32_e32 v204, 0x1d440, v195
	ds_read_b128 v[204:207], v204
	v_mad_i32_i24 v208, v167, s38, v35
	v_add_u32_e32 v128, 0x1d400, v208
	ds_read_b128 v[128:131], v128
	v_mad_i32_i24 v209, v166, s38, v35
	v_add_u32_e32 v196, 0x1d400, v209
	ds_read_b128 v[196:199], v196
	s_waitcnt vmcnt(11) lgkmcnt(3)
	v_mfma_f32_16x16x32_bf16 v[124:127], v[124:127], v[40:43], 0
	v_mad_i32_i24 v35, v165, s38, v35
	v_add_u32_e32 v200, 0x1d400, v35
	ds_read_b128 v[200:203], v200
	s_waitcnt vmcnt(16) lgkmcnt(3)
	v_mfma_f32_16x16x32_bf16 v[124:127], v[204:207], v[24:27], v[124:127]
	v_add_u32_e32 v204, 0x1d440, v208
	ds_read_b128 v[204:207], v204
	v_xor_b32_e32 v212, 0x80, v194
	s_waitcnt lgkmcnt(3)
	v_mfma_f32_16x16x32_bf16 v[128:131], v[128:131], v[40:43], 0
	v_cmp_gt_u32_e32 vcc, 16, v151
	s_waitcnt lgkmcnt(2)
	v_mfma_f32_16x16x32_bf16 v[196:199], v[196:199], v[40:43], 0
	s_waitcnt lgkmcnt(0)
	v_mfma_f32_16x16x32_bf16 v[128:131], v[204:207], v[24:27], v[128:131]
	v_add_u32_e32 v204, 0x1d440, v209
	ds_read_b128 v[204:207], v204
	v_mfma_f32_16x16x32_bf16 v[200:203], v[200:203], v[40:43], 0
	s_waitcnt lgkmcnt(0)
	v_mfma_f32_16x16x32_bf16 v[196:199], v[204:207], v[24:27], v[196:199]
	v_add_u32_e32 v204, 0x1d440, v35
	ds_read_b128 v[204:207], v204
	s_waitcnt lgkmcnt(0)
	v_mfma_f32_16x16x32_bf16 v[200:203], v[204:207], v[24:27], v[200:203]
	v_add_u32_e32 v204, 0x1d480, v195
	ds_read_b128 v[204:207], v204
	s_waitcnt vmcnt(15) lgkmcnt(0)
	v_mfma_f32_16x16x32_bf16 v[124:127], v[204:207], v[28:31], v[124:127]
	v_add_u32_e32 v204, 0x1d480, v208
	ds_read_b128 v[204:207], v204
	s_waitcnt lgkmcnt(0)
	v_mfma_f32_16x16x32_bf16 v[128:131], v[204:207], v[28:31], v[128:131]
	v_add_u32_e32 v204, 0x1d480, v209
	ds_read_b128 v[204:207], v204
	s_waitcnt lgkmcnt(0)
	v_mfma_f32_16x16x32_bf16 v[196:199], v[204:207], v[28:31], v[196:199]
	v_add_u32_e32 v204, 0x1d480, v35
	ds_read_b128 v[204:207], v204
	s_waitcnt lgkmcnt(0)
	v_mfma_f32_16x16x32_bf16 v[200:203], v[204:207], v[28:31], v[200:203]
	v_add_u32_e32 v204, 0x1d4c0, v195
	ds_read_b128 v[204:207], v204
	s_waitcnt vmcnt(14) lgkmcnt(0)
	v_mfma_f32_16x16x32_bf16 v[124:127], v[204:207], v[36:39], v[124:127]
	v_add_u32_e32 v204, 0x1d4c0, v208
	ds_read_b128 v[204:207], v204
	s_waitcnt lgkmcnt(0)
	v_mfma_f32_16x16x32_bf16 v[128:131], v[204:207], v[36:39], v[128:131]
	v_add_u32_e32 v204, 0x1d4c0, v209
	ds_read_b128 v[204:207], v204
	s_waitcnt lgkmcnt(0)
	v_mfma_f32_16x16x32_bf16 v[196:199], v[204:207], v[36:39], v[196:199]
	v_add_u32_e32 v204, 0x1d4c0, v35
	ds_read_b128 v[204:207], v204
	s_waitcnt lgkmcnt(0)
	v_mfma_f32_16x16x32_bf16 v[200:203], v[204:207], v[36:39], v[200:203]
	v_add_u32_e32 v204, 0x1d500, v195
	ds_read_b128 v[204:207], v204
	s_waitcnt vmcnt(13) lgkmcnt(0)
	v_mfma_f32_16x16x32_bf16 v[124:127], v[204:207], v[44:47], v[124:127]
	v_add_u32_e32 v204, 0x1d500, v208
	ds_read_b128 v[204:207], v204
	s_waitcnt lgkmcnt(0)
	v_mfma_f32_16x16x32_bf16 v[128:131], v[204:207], v[44:47], v[128:131]
	v_add_u32_e32 v204, 0x1d500, v209
	ds_read_b128 v[204:207], v204
	s_waitcnt lgkmcnt(0)
	v_mfma_f32_16x16x32_bf16 v[196:199], v[204:207], v[44:47], v[196:199]
	v_add_u32_e32 v204, 0x1d500, v35
	ds_read_b128 v[204:207], v204
	s_waitcnt lgkmcnt(0)
	v_mfma_f32_16x16x32_bf16 v[200:203], v[204:207], v[44:47], v[200:203]
	v_add_u32_e32 v204, 0x1d540, v195
	ds_read_b128 v[204:207], v204
	s_waitcnt vmcnt(12) lgkmcnt(0)
	v_mfma_f32_16x16x32_bf16 v[124:127], v[204:207], v[52:55], v[124:127]
	v_add_u32_e32 v204, 0x1d540, v208
	ds_read_b128 v[204:207], v204
	s_waitcnt lgkmcnt(0)
	v_mfma_f32_16x16x32_bf16 v[128:131], v[204:207], v[52:55], v[128:131]
	v_add_u32_e32 v204, 0x1d540, v209
	ds_read_b128 v[204:207], v204
	s_waitcnt lgkmcnt(0)
	v_mfma_f32_16x16x32_bf16 v[196:199], v[204:207], v[52:55], v[196:199]
	v_add_u32_e32 v204, 0x1d540, v35
	ds_read_b128 v[204:207], v204
	s_waitcnt lgkmcnt(0)
	v_mfma_f32_16x16x32_bf16 v[200:203], v[204:207], v[52:55], v[200:203]
	v_add_u32_e32 v204, 0x1d580, v195
	ds_read_b128 v[204:207], v204
	v_add_u32_e32 v195, 0x1d5c0, v195
	s_waitcnt vmcnt(11) lgkmcnt(0)
	v_mfma_f32_16x16x32_bf16 v[124:127], v[204:207], v[56:59], v[124:127]
	v_add_u32_e32 v204, 0x1d580, v208
	ds_read_b128 v[204:207], v204
	s_waitcnt lgkmcnt(0)
	v_mfma_f32_16x16x32_bf16 v[128:131], v[204:207], v[56:59], v[128:131]
	v_add_u32_e32 v204, 0x1d580, v209
	ds_read_b128 v[204:207], v204
	s_waitcnt lgkmcnt(0)
	v_mfma_f32_16x16x32_bf16 v[196:199], v[204:207], v[56:59], v[196:199]
	v_add_u32_e32 v204, 0x1d580, v35
	ds_read_b128 v[204:207], v204
	v_add_u32_e32 v35, 0x1d5c0, v35
	s_waitcnt lgkmcnt(0)
	v_mfma_f32_16x16x32_bf16 v[200:203], v[204:207], v[56:59], v[200:203]
	ds_read_b128 v[204:207], v195
	v_add_u32_e32 v195, 0x1d5c0, v208
	s_waitcnt vmcnt(10) lgkmcnt(0)
	v_mfma_f32_16x16x32_bf16 v[124:127], v[204:207], v[60:63], v[124:127]
	ds_read_b128 v[204:207], v195
	v_add_u32_e32 v195, 0x1d5c0, v209
	s_waitcnt lgkmcnt(0)
	v_mfma_f32_16x16x32_bf16 v[128:131], v[204:207], v[60:63], v[128:131]
	ds_read_b128 v[204:207], v195
	s_waitcnt lgkmcnt(0)
	v_mfma_f32_16x16x32_bf16 v[196:199], v[204:207], v[60:63], v[196:199]
	ds_read_b128 v[204:207], v35
	v_add_u32_e32 v35, 1, v34
	v_cvt_f32_i32_e32 v35, v35
	s_waitcnt lgkmcnt(0)
	v_mfma_f32_16x16x32_bf16 v[200:203], v[204:207], v[60:63], v[200:203]
	v_mul_f32_e32 v35, v147, v35
	v_exp_f32_e32 v204, v35
	v_ashrrev_i32_e32 v35, 31, v34
	v_lshl_add_u64 v[34:35], s[42:43], 0, v[34:35]
	v_lshlrev_b64 v[206:207], 12, v[34:35]
	v_pk_fma_f32 v[122:123], v[204:205], v[126:127], v[122:123] op_sel_hi:[0,1,1]
	v_lshl_add_u64 v[206:207], s[46:47], 0, v[206:207]
	v_pk_fma_f32 v[120:121], v[204:205], v[124:125], v[120:121] op_sel_hi:[0,1,1]
	v_mul_f32_e32 v205, v122, v122
	v_lshl_add_u64 v[206:207], v[32:33], 1, v[206:207]
	v_cvt_pk_bf16_f32 v124, v120, v121
	v_cvt_pk_bf16_f32 v125, v122, v123
	v_pk_fma_f32 v[118:119], v[204:205], v[130:131], v[118:119] op_sel_hi:[0,1,1]
	v_pk_fma_f32 v[116:117], v[204:205], v[128:129], v[116:117] op_sel_hi:[0,1,1]
	global_store_dwordx2 v[206:207], v[124:125], off
	v_add_f32_e32 v124, v120, v121
	v_mul_f32_e32 v195, v120, v120
	v_mul_f32_e32 v121, v121, v121
	v_cvt_pk_bf16_f32 v128, v116, v117
	v_cvt_pk_bf16_f32 v129, v118, v119
	v_mul_f32_e32 v120, v118, v118
	v_add_f32_e32 v126, v122, v123
	v_mul_f32_e32 v123, v123, v123
	global_store_dwordx2 v[206:207], v[128:129], off offset:32
	v_pk_fma_f32 v[128:129], v[118:119], v[118:119], v[120:121] op_sel_hi:[1,1,0]
	v_pk_fma_f32 v[114:115], v[204:205], v[198:199], v[114:115] op_sel_hi:[0,1,1]
	v_pk_fma_f32 v[112:113], v[204:205], v[196:197], v[112:113] op_sel_hi:[0,1,1]
	v_pk_fma_f32 v[110:111], v[204:205], v[202:203], v[110:111] op_sel_hi:[0,1,1]
	v_pk_fma_f32 v[108:109], v[204:205], v[200:201], v[108:109] op_sel_hi:[0,1,1]
	v_mov_b32_e32 v194, v116
	v_mov_b32_e32 v120, v117
	v_mov_b32_e32 v204, v118
	v_mov_b32_e32 v122, v119
	v_mul_f32_e32 v125, v116, v116
	v_mul_f32_e32 v127, v117, v117
	v_cvt_pk_bf16_f32 v130, v112, v113
	v_cvt_pk_bf16_f32 v131, v114, v115
	v_pk_add_f32 v[116:117], v[194:195], v[120:121]
	v_pk_add_f32 v[118:119], v[204:205], v[122:123]
	global_store_dwordx2 v[206:207], v[130:131], off offset:64
	v_mul_f32_e32 v131, v112, v112
	v_mul_f32_e32 v197, v113, v113
	v_mul_f32_e32 v199, v114, v114
	v_mul_f32_e32 v209, v115, v115
	v_cvt_pk_bf16_f32 v200, v108, v109
	v_cvt_pk_bf16_f32 v201, v110, v111
	v_pk_add_f32 v[116:117], v[116:117], v[118:119]
	v_pk_add_f32 v[118:119], v[124:125], v[126:127]
	v_mov_b32_e32 v128, v33
	v_mov_b32_e32 v130, v112
	v_mov_b32_e32 v196, v113
	v_mov_b32_e32 v198, v114
	v_mov_b32_e32 v208, v115
	global_store_dwordx2 v[206:207], v[200:201], off offset:96
	v_mul_f32_e32 v201, v108, v108
	v_mul_f32_e32 v203, v109, v109
	v_mul_f32_e32 v207, v110, v110
	v_mul_f32_e32 v211, v111, v111
	v_pk_add_f32 v[118:119], v[118:119], v[128:129]
	v_pk_add_f32 v[112:113], v[130:131], v[196:197]
	v_pk_add_f32 v[114:115], v[198:199], v[208:209]
	v_mov_b32_e32 v200, v108
	v_mov_b32_e32 v202, v109
	v_mov_b32_e32 v206, v110
	v_mov_b32_e32 v210, v111
	v_pk_add_f32 v[116:117], v[116:117], v[118:119]
	v_pk_add_f32 v[112:113], v[112:113], v[114:115]
	v_pk_add_f32 v[108:109], v[200:201], v[202:203]
	v_pk_add_f32 v[110:111], v[206:207], v[210:211]
	v_pk_add_f32 v[112:113], v[116:117], v[112:113]
	v_pk_add_f32 v[108:109], v[108:109], v[110:111]
	s_nop 0
	v_pk_add_f32 v[108:109], v[112:113], v[108:109]
	ds_swizzle_b32 v110, v108 offset:swizzle(SWAP,16)
	ds_swizzle_b32 v111, v109 offset:swizzle(SWAP,16)
	s_waitcnt lgkmcnt(0)
	v_pk_add_f32 v[108:109], v[108:109], v[110:111]
	ds_bpermute_b32 v110, v212, v108
	ds_bpermute_b32 v111, v212, v109
	s_and_saveexec_b64 s[42:43], vcc
	s_cbranch_execz .LBB0_213
	v_lshlrev_b64 v[112:113], 8, v[34:35]
	v_lshl_add_u64 v[112:113], s[50:51], 0, v[112:113]
	s_waitcnt lgkmcnt(0)
	v_pk_add_f32 v[108:109], v[108:109], v[110:111]
	global_store_dwordx2 v[112:113], v[108:109], off

.LBB0_267:
	s_ashr_i32 s0, s35, 1
	s_lshl_b32 s0, s0, 6
	s_add_u32 s0, s74, s0
	s_addc_u32 s1, s75, 0
	s_lshl_b32 s82, s34, 16
	v_lshl_or_b32 v154, v137, 8, v177
	v_add_u32_e32 v154, s82, v154
	global_load_dwordx4 v[210:213], v154, s[0:1]
	v_add_u32_e32 v155, 0x1000, v154
	global_load_dwordx4 v[214:217], v155, s[0:1]
	v_add_u32_e32 v155, 0x2000, v154
	global_load_dwordx4 v[218:221], v155, s[0:1]
	v_add_u32_e32 v155, 0x3000, v154
	global_load_dwordx4 v[222:225], v155, s[0:1]
	v_add_u32_e32 v155, 0x8000, v154
	global_load_dwordx4 v[226:229], v155, s[0:1]
	v_add_u32_e32 v155, 0x9000, v154
	global_load_dwordx4 v[230:233], v155, s[0:1]
	v_add_u32_e32 v155, 0xa000, v154
	global_load_dwordx4 v[234:237], v155, s[0:1]
	v_add_u32_e32 v155, 0xb000, v154
	global_load_dwordx4 v[238:241], v155, s[0:1]
	s_lshl_b32 s82, s34, 8
	v_add_u32_e32 v156, s82, v137
	v_mul_lo_u32 v156, v156, s17
	s_lshl_b32 s82, s35, 8
	v_add_u32_e32 v158, s82, v157
	v_add_lshl_u32 v156, v156, v158, 1
	s_lshl_b32 s82, s17, 5
	global_load_dwordx4 v[162:165], v156, s[58:59]
	global_load_dwordx4 v[166:169], v156, s[58:59] offset:256
	s_mul_i32 s83, s82, 1
	v_add_u32_e32 v158, s83, v156
	global_load_dwordx4 v[130:133], v158, s[58:59]
	global_load_dwordx4 v[150:153], v158, s[58:59] offset:256
	v_xor_b32_e32 v159, 32, v135
	v_lshlrev_b32_e32 v159, 2, v159
	s_waitcnt vmcnt(4)
	v_add_f32_e32 v194, v211, v213
	v_add_f32_e32 v195, v210, v212
	v_add_f32_e32 v196, v215, v217
	v_add_f32_e32 v197, v214, v216
	v_add_f32_e32 v198, v219, v221
	v_add_f32_e32 v199, v218, v220
	v_add_f32_e32 v200, v223, v225
	v_add_f32_e32 v201, v222, v224
	v_add_f32_e32 v202, v227, v229
	v_add_f32_e32 v203, v226, v228
	v_add_f32_e32 v204, v231, v233
	v_add_f32_e32 v205, v230, v232
	v_add_f32_e32 v206, v235, v237
	v_add_f32_e32 v207, v234, v236
	v_add_f32_e32 v208, v239, v241
	v_add_f32_e32 v209, v238, v240
	ds_swizzle_b32 v210, v194 offset:swizzle(SWAP,16)
	ds_swizzle_b32 v211, v195 offset:swizzle(SWAP,16)
	ds_swizzle_b32 v212, v196 offset:swizzle(SWAP,16)
	ds_swizzle_b32 v213, v197 offset:swizzle(SWAP,16)
	ds_swizzle_b32 v214, v198 offset:swizzle(SWAP,16)
	ds_swizzle_b32 v215, v199 offset:swizzle(SWAP,16)
	ds_swizzle_b32 v216, v200 offset:swizzle(SWAP,16)
	ds_swizzle_b32 v217, v201 offset:swizzle(SWAP,16)
	s_waitcnt lgkmcnt(0)
	v_add_f32_e32 v194, v194, v210
	v_add_f32_e32 v195, v195, v211
	v_add_f32_e32 v196, v196, v212
	v_add_f32_e32 v197, v197, v213
	v_add_f32_e32 v198, v198, v214
	v_add_f32_e32 v199, v199, v215
	v_add_f32_e32 v200, v200, v216
	v_add_f32_e32 v201, v201, v217
	ds_bpermute_b32 v210, v159, v194
	ds_bpermute_b32 v211, v159, v195
	ds_bpermute_b32 v212, v159, v196
	ds_bpermute_b32 v213, v159, v197
	ds_bpermute_b32 v214, v159, v198
	ds_bpermute_b32 v215, v159, v199
	ds_bpermute_b32 v216, v159, v200
	ds_bpermute_b32 v217, v159, v201
	s_waitcnt lgkmcnt(0)
	v_add_f32_e32 v194, v194, v210
	v_add_f32_e32 v195, v195, v211
	v_add_f32_e32 v196, v196, v212
	v_add_f32_e32 v197, v197, v213
	v_add_f32_e32 v198, v198, v214
	v_add_f32_e32 v199, v199, v215
	v_add_f32_e32 v200, v200, v216
	v_add_f32_e32 v201, v201, v217
	ds_swizzle_b32 v210, v202 offset:swizzle(SWAP,16)
	ds_swizzle_b32 v211, v203 offset:swizzle(SWAP,16)
	ds_swizzle_b32 v212, v204 offset:swizzle(SWAP,16)
	ds_swizzle_b32 v213, v205 offset:swizzle(SWAP,16)
	ds_swizzle_b32 v214, v206 offset:swizzle(SWAP,16)
	ds_swizzle_b32 v215, v207 offset:swizzle(SWAP,16)
	ds_swizzle_b32 v216, v208 offset:swizzle(SWAP,16)
	ds_swizzle_b32 v217, v209 offset:swizzle(SWAP,16)
	s_waitcnt lgkmcnt(0)
	v_add_f32_e32 v202, v202, v210
	v_add_f32_e32 v203, v203, v211
	v_add_f32_e32 v204, v204, v212
	v_add_f32_e32 v205, v205, v213
	v_add_f32_e32 v206, v206, v214
	v_add_f32_e32 v207, v207, v215
	v_add_f32_e32 v208, v208, v216
	v_add_f32_e32 v209, v209, v217
	ds_bpermute_b32 v210, v159, v202
	ds_bpermute_b32 v211, v159, v203
	ds_bpermute_b32 v212, v159, v204
	ds_bpermute_b32 v213, v159, v205
	ds_bpermute_b32 v214, v159, v206
	ds_bpermute_b32 v215, v159, v207
	ds_bpermute_b32 v216, v159, v208
	ds_bpermute_b32 v217, v159, v209
	s_waitcnt lgkmcnt(0)
	v_add_f32_e32 v202, v202, v210
	v_add_f32_e32 v203, v203, v211
	v_add_f32_e32 v204, v204, v212
	v_add_f32_e32 v205, v205, v213
	v_add_f32_e32 v206, v206, v214
	v_add_f32_e32 v207, v207, v215
	v_add_f32_e32 v208, v208, v216
	v_add_f32_e32 v209, v209, v217
	v_pk_mul_f32 v[194:195], v[194:195], s[24:25] op_sel_hi:[1,0]
	s_nop 0
	v_fma_f32 v154, -v195, v195, v194
	v_max_f32_e32 v154, 0, v154
	v_add_f32_e32 v154, 0x358637bd, v154
	v_cmp_gt_f32_e32 vcc, s37, v154
	v_mul_f32_e32 v155, 0x4b800000, v154
	s_nop 0
	v_cndmask_b32_e32 v154, v154, v155, vcc
	v_rsq_f32_e32 v154, v154
	s_nop 0
	v_mul_f32_e32 v155, 0x45800000, v154
	v_cndmask_b32_e32 v194, v154, v155, vcc
	v_pk_mul_f32 v[196:197], v[196:197], s[24:25] op_sel_hi:[1,0]
	s_nop 0
	v_fma_f32 v154, -v197, v197, v196
	v_max_f32_e32 v154, 0, v154
	v_add_f32_e32 v154, 0x358637bd, v154
	v_cmp_gt_f32_e32 vcc, s37, v154
	v_mul_f32_e32 v155, 0x4b800000, v154
	s_nop 0
	v_cndmask_b32_e32 v154, v154, v155, vcc
	v_rsq_f32_e32 v154, v154
	s_nop 0
	v_mul_f32_e32 v155, 0x45800000, v154
	v_cndmask_b32_e32 v196, v154, v155, vcc
	v_pk_mul_f32 v[198:199], v[198:199], s[24:25] op_sel_hi:[1,0]
	s_nop 0
	v_fma_f32 v154, -v199, v199, v198
	v_max_f32_e32 v154, 0, v154
	v_add_f32_e32 v154, 0x358637bd, v154
	v_cmp_gt_f32_e32 vcc, s37, v154
	v_mul_f32_e32 v155, 0x4b800000, v154
	s_nop 0
	v_cndmask_b32_e32 v154, v154, v155, vcc
	v_rsq_f32_e32 v154, v154
	s_nop 0
	v_mul_f32_e32 v155, 0x45800000, v154
	v_cndmask_b32_e32 v198, v154, v155, vcc
	v_pk_mul_f32 v[200:201], v[200:201], s[24:25] op_sel_hi:[1,0]
	s_nop 0
	v_fma_f32 v154, -v201, v201, v200
	v_max_f32_e32 v154, 0, v154
	v_add_f32_e32 v154, 0x358637bd, v154
	v_cmp_gt_f32_e32 vcc, s37, v154
	v_mul_f32_e32 v155, 0x4b800000, v154
	s_nop 0
	v_cndmask_b32_e32 v154, v154, v155, vcc
	v_rsq_f32_e32 v154, v154
	s_nop 0
	v_mul_f32_e32 v155, 0x45800000, v154
	v_cndmask_b32_e32 v200, v154, v155, vcc
	v_pk_mul_f32 v[202:203], v[202:203], s[24:25] op_sel_hi:[1,0]
	s_nop 0
	v_fma_f32 v154, -v203, v203, v202
	v_max_f32_e32 v154, 0, v154
	v_add_f32_e32 v154, 0x358637bd, v154
	v_cmp_gt_f32_e32 vcc, s37, v154
	v_mul_f32_e32 v155, 0x4b800000, v154
	s_nop 0
	v_cndmask_b32_e32 v154, v154, v155, vcc
	v_rsq_f32_e32 v154, v154
	s_nop 0
	v_mul_f32_e32 v155, 0x45800000, v154
	v_cndmask_b32_e32 v202, v154, v155, vcc
	v_pk_mul_f32 v[204:205], v[204:205], s[24:25] op_sel_hi:[1,0]
	s_nop 0
	v_fma_f32 v154, -v205, v205, v204
	v_max_f32_e32 v154, 0, v154
	v_add_f32_e32 v154, 0x358637bd, v154
	v_cmp_gt_f32_e32 vcc, s37, v154
	v_mul_f32_e32 v155, 0x4b800000, v154
	s_nop 0
	v_cndmask_b32_e32 v154, v154, v155, vcc
	v_rsq_f32_e32 v154, v154
	s_nop 0
	v_mul_f32_e32 v155, 0x45800000, v154
	v_cndmask_b32_e32 v204, v154, v155, vcc
	v_pk_mul_f32 v[206:207], v[206:207], s[24:25] op_sel_hi:[1,0]
	s_nop 0
	v_fma_f32 v154, -v207, v207, v206
	v_max_f32_e32 v154, 0, v154
	v_add_f32_e32 v154, 0x358637bd, v154
	v_cmp_gt_f32_e32 vcc, s37, v154
	v_mul_f32_e32 v155, 0x4b800000, v154
	s_nop 0
	v_cndmask_b32_e32 v154, v154, v155, vcc
	v_rsq_f32_e32 v154, v154
	s_nop 0
	v_mul_f32_e32 v155, 0x45800000, v154
	v_cndmask_b32_e32 v206, v154, v155, vcc
	v_pk_mul_f32 v[208:209], v[208:209], s[24:25] op_sel_hi:[1,0]
	s_nop 0
	v_fma_f32 v154, -v209, v209, v208
	v_max_f32_e32 v154, 0, v154
	v_add_f32_e32 v154, 0x358637bd, v154
	v_cmp_gt_f32_e32 vcc, s37, v154
	v_mul_f32_e32 v155, 0x4b800000, v154
	s_nop 0
	v_cndmask_b32_e32 v154, v154, v155, vcc
	v_rsq_f32_e32 v154, v154
	s_nop 0
	v_mul_f32_e32 v155, 0x45800000, v154
	v_cndmask_b32_e32 v208, v154, v155, vcc
	s_mul_i32 s83, s82, 2
	v_add_u32_e32 v154, s83, v156
	global_load_dwordx4 v[210:213], v154, s[58:59]
	global_load_dwordx4 v[214:217], v154, s[58:59] offset:256
	s_mul_i32 s83, s82, 3
	v_add_u32_e32 v154, s83, v156
	global_load_dwordx4 v[218:221], v154, s[58:59]
	global_load_dwordx4 v[222:225], v154, s[58:59] offset:256
	s_mul_i32 s83, s82, 8
	v_add_u32_e32 v154, s83, v156
	global_load_dwordx4 v[226:229], v154, s[58:59]
	global_load_dwordx4 v[230:233], v154, s[58:59] offset:256
	s_mul_i32 s83, s82, 9
	v_add_u32_e32 v154, s83, v156
	global_load_dwordx4 v[234:237], v154, s[58:59]
	global_load_dwordx4 v[238:241], v154, s[58:59] offset:256
	s_waitcnt vmcnt(10)
	v_mul_f32_e32 v154, 0xbfb8aa3b, v126
	v_mul_f32_e32 v155, 0xbfb8aa3b, v127
	v_exp_f32_e32 v154, v154
	v_exp_f32_e32 v155, v155
	v_lshlrev_b32_e32 v158, 16, v162
	v_and_b32_e32 v159, 0xffff0000, v162
	v_add_f32_e32 v154, 1.0, v154
	v_add_f32_e32 v155, 1.0, v155
	v_rcp_f32_e32 v154, v154
	v_rcp_f32_e32 v155, v155
	v_pk_add_f32 v[158:159], v[158:159], v[194:195] op_sel:[0,1] neg_lo:[0,1] neg_hi:[0,1]
	s_nop 0
	v_pk_mul_f32 v[158:159], v[158:159], v[194:195] op_sel_hi:[1,0]
	v_pk_mul_f32 v[126:127], v[126:127], v[154:155]
	s_nop 0
	v_pk_mul_f32 v[126:127], v[126:127], v[158:159]
	s_nop 0
	v_cvt_pk_bf16_f32 v162, v126, v127
	v_mul_f32_e32 v154, 0xbfb8aa3b, v128
	v_mul_f32_e32 v155, 0xbfb8aa3b, v129
	v_exp_f32_e32 v154, v154
	v_exp_f32_e32 v155, v155
	v_lshlrev_b32_e32 v158, 16, v163
	v_and_b32_e32 v159, 0xffff0000, v163
	v_add_f32_e32 v154, 1.0, v154
	v_add_f32_e32 v155, 1.0, v155
	v_rcp_f32_e32 v154, v154
	v_rcp_f32_e32 v155, v155
	v_pk_add_f32 v[158:159], v[158:159], v[194:195] op_sel:[0,1] neg_lo:[0,1] neg_hi:[0,1]
	s_nop 0
	v_pk_mul_f32 v[158:159], v[158:159], v[194:195] op_sel_hi:[1,0]
	v_pk_mul_f32 v[128:129], v[128:129], v[154:155]
	s_nop 0
	v_pk_mul_f32 v[128:129], v[128:129], v[158:159]
	s_nop 0
	v_cvt_pk_bf16_f32 v163, v128, v129
	v_mul_f32_e32 v154, 0xbfb8aa3b, v122
	v_mul_f32_e32 v155, 0xbfb8aa3b, v123
	v_exp_f32_e32 v154, v154
	v_exp_f32_e32 v155, v155
	v_lshlrev_b32_e32 v158, 16, v164
	v_and_b32_e32 v159, 0xffff0000, v164
	v_add_f32_e32 v154, 1.0, v154
	v_add_f32_e32 v155, 1.0, v155
	v_rcp_f32_e32 v154, v154
	v_rcp_f32_e32 v155, v155
	v_pk_add_f32 v[158:159], v[158:159], v[194:195] op_sel:[0,1] neg_lo:[0,1] neg_hi:[0,1]
	s_nop 0
	v_pk_mul_f32 v[158:159], v[158:159], v[194:195] op_sel_hi:[1,0]
	v_pk_mul_f32 v[122:123], v[122:123], v[154:155]
	s_nop 0
	v_pk_mul_f32 v[122:123], v[122:123], v[158:159]
	s_nop 0
	v_cvt_pk_bf16_f32 v164, v122, v123
	v_mul_f32_e32 v154, 0xbfb8aa3b, v124
	v_mul_f32_e32 v155, 0xbfb8aa3b, v125
	v_exp_f32_e32 v154, v154
	v_exp_f32_e32 v155, v155
	v_lshlrev_b32_e32 v158, 16, v165
	v_and_b32_e32 v159, 0xffff0000, v165
	v_add_f32_e32 v154, 1.0, v154
	v_add_f32_e32 v155, 1.0, v155
	v_rcp_f32_e32 v154, v154
	v_rcp_f32_e32 v155, v155
	v_pk_add_f32 v[158:159], v[158:159], v[194:195] op_sel:[0,1] neg_lo:[0,1] neg_hi:[0,1]
	s_nop 0
	v_pk_mul_f32 v[158:159], v[158:159], v[194:195] op_sel_hi:[1,0]
	v_pk_mul_f32 v[124:125], v[124:125], v[154:155]
	s_nop 0
	v_pk_mul_f32 v[124:125], v[124:125], v[158:159]
	s_nop 0
	v_cvt_pk_bf16_f32 v165, v124, v125
	v_mul_f32_e32 v154, 0xbfb8aa3b, v118
	v_mul_f32_e32 v155, 0xbfb8aa3b, v119
	v_exp_f32_e32 v154, v154
	v_exp_f32_e32 v155, v155
	v_lshlrev_b32_e32 v158, 16, v166
	v_and_b32_e32 v159, 0xffff0000, v166
	v_add_f32_e32 v154, 1.0, v154
	v_add_f32_e32 v155, 1.0, v155
	v_rcp_f32_e32 v154, v154
	v_rcp_f32_e32 v155, v155
	v_pk_add_f32 v[158:159], v[158:159], v[194:195] op_sel:[0,1] neg_lo:[0,1] neg_hi:[0,1]
	s_nop 0
	v_pk_mul_f32 v[158:159], v[158:159], v[194:195] op_sel_hi:[1,0]
	v_pk_mul_f32 v[118:119], v[118:119], v[154:155]
	s_nop 0
	v_pk_mul_f32 v[118:119], v[118:119], v[158:159]
	s_nop 0
	v_cvt_pk_bf16_f32 v166, v118, v119
	v_mul_f32_e32 v154, 0xbfb8aa3b, v120
	v_mul_f32_e32 v155, 0xbfb8aa3b, v121
	v_exp_f32_e32 v154, v154
	v_exp_f32_e32 v155, v155
	v_lshlrev_b32_e32 v158, 16, v167
	v_and_b32_e32 v159, 0xffff0000, v167
	v_add_f32_e32 v154, 1.0, v154
	v_add_f32_e32 v155, 1.0, v155
	v_rcp_f32_e32 v154, v154
	v_rcp_f32_e32 v155, v155
	v_pk_add_f32 v[158:159], v[158:159], v[194:195] op_sel:[0,1] neg_lo:[0,1] neg_hi:[0,1]
	s_nop 0
	v_pk_mul_f32 v[158:159], v[158:159], v[194:195] op_sel_hi:[1,0]
	v_pk_mul_f32 v[120:121], v[120:121], v[154:155]
	s_nop 0
	v_pk_mul_f32 v[120:121], v[120:121], v[158:159]
	s_nop 0
	v_cvt_pk_bf16_f32 v167, v120, v121
	v_mul_f32_e32 v154, 0xbfb8aa3b, v114
	v_mul_f32_e32 v155, 0xbfb8aa3b, v115
	v_exp_f32_e32 v154, v154
	v_exp_f32_e32 v155, v155
	v_lshlrev_b32_e32 v158, 16, v168
	v_and_b32_e32 v159, 0xffff0000, v168
	v_add_f32_e32 v154, 1.0, v154
	v_add_f32_e32 v155, 1.0, v155
	v_rcp_f32_e32 v154, v154
	v_rcp_f32_e32 v155, v155
	v_pk_add_f32 v[158:159], v[158:159], v[194:195] op_sel:[0,1] neg_lo:[0,1] neg_hi:[0,1]
	s_nop 0
	v_pk_mul_f32 v[158:159], v[158:159], v[194:195] op_sel_hi:[1,0]
	v_pk_mul_f32 v[114:115], v[114:115], v[154:155]
	s_nop 0
	v_pk_mul_f32 v[114:115], v[114:115], v[158:159]
	s_nop 0
	v_cvt_pk_bf16_f32 v168, v114, v115
	v_mul_f32_e32 v154, 0xbfb8aa3b, v116
	v_mul_f32_e32 v155, 0xbfb8aa3b, v117
	v_exp_f32_e32 v154, v154
	v_exp_f32_e32 v155, v155
	v_lshlrev_b32_e32 v158, 16, v169
	v_and_b32_e32 v159, 0xffff0000, v169
	v_add_f32_e32 v154, 1.0, v154
	v_add_f32_e32 v155, 1.0, v155
	v_rcp_f32_e32 v154, v154
	v_rcp_f32_e32 v155, v155
	v_pk_add_f32 v[158:159], v[158:159], v[194:195] op_sel:[0,1] neg_lo:[0,1] neg_hi:[0,1]
	s_nop 0
	v_pk_mul_f32 v[158:159], v[158:159], v[194:195] op_sel_hi:[1,0]
	v_pk_mul_f32 v[116:117], v[116:117], v[154:155]
	s_nop 0
	v_pk_mul_f32 v[116:117], v[116:117], v[158:159]
	s_nop 0
	v_cvt_pk_bf16_f32 v169, v116, v117
	global_store_dwordx4 v156, v[162:165], s[58:59]
	global_store_dwordx4 v156, v[166:169], s[58:59] offset:256
	s_mul_i32 s83, s82, 10
	v_add_u32_e32 v154, s83, v156
	global_load_dwordx4 v[162:165], v154, s[58:59]
	global_load_dwordx4 v[166:169], v154, s[58:59] offset:256
	s_waitcnt vmcnt(12)
	v_mul_f32_e32 v154, 0xbfb8aa3b, v110
	v_mul_f32_e32 v155, 0xbfb8aa3b, v111
	v_exp_f32_e32 v154, v154
	v_exp_f32_e32 v155, v155
	v_lshlrev_b32_e32 v158, 16, v130
	v_and_b32_e32 v159, 0xffff0000, v130
	v_add_f32_e32 v154, 1.0, v154
	v_add_f32_e32 v155, 1.0, v155
	v_rcp_f32_e32 v154, v154
	v_rcp_f32_e32 v155, v155
	v_pk_add_f32 v[158:159], v[158:159], v[196:197] op_sel:[0,1] neg_lo:[0,1] neg_hi:[0,1]
	s_nop 0
	v_pk_mul_f32 v[158:159], v[158:159], v[196:197] op_sel_hi:[1,0]
	v_pk_mul_f32 v[110:111], v[110:111], v[154:155]
	s_nop 0
	v_pk_mul_f32 v[110:111], v[110:111], v[158:159]
	s_nop 0
	v_cvt_pk_bf16_f32 v130, v110, v111
	v_mul_f32_e32 v154, 0xbfb8aa3b, v112
	v_mul_f32_e32 v155, 0xbfb8aa3b, v113
	v_exp_f32_e32 v154, v154
	v_exp_f32_e32 v155, v155
	v_lshlrev_b32_e32 v158, 16, v131
	v_and_b32_e32 v159, 0xffff0000, v131
	v_add_f32_e32 v154, 1.0, v154
	v_add_f32_e32 v155, 1.0, v155
	v_rcp_f32_e32 v154, v154
	v_rcp_f32_e32 v155, v155
	v_pk_add_f32 v[158:159], v[158:159], v[196:197] op_sel:[0,1] neg_lo:[0,1] neg_hi:[0,1]
	s_nop 0
	v_pk_mul_f32 v[158:159], v[158:159], v[196:197] op_sel_hi:[1,0]
	v_pk_mul_f32 v[112:113], v[112:113], v[154:155]
	s_nop 0
	v_pk_mul_f32 v[112:113], v[112:113], v[158:159]
	s_nop 0
	v_cvt_pk_bf16_f32 v131, v112, v113
	v_mul_f32_e32 v154, 0xbfb8aa3b, v106
	v_mul_f32_e32 v155, 0xbfb8aa3b, v107
	v_exp_f32_e32 v154, v154
	v_exp_f32_e32 v155, v155
	v_lshlrev_b32_e32 v158, 16, v132
	v_and_b32_e32 v159, 0xffff0000, v132
	v_add_f32_e32 v154, 1.0, v154
	v_add_f32_e32 v155, 1.0, v155
	v_rcp_f32_e32 v154, v154
	v_rcp_f32_e32 v155, v155
	v_pk_add_f32 v[158:159], v[158:159], v[196:197] op_sel:[0,1] neg_lo:[0,1] neg_hi:[0,1]
	s_nop 0
	v_pk_mul_f32 v[158:159], v[158:159], v[196:197] op_sel_hi:[1,0]
	v_pk_mul_f32 v[106:107], v[106:107], v[154:155]
	s_nop 0
	v_pk_mul_f32 v[106:107], v[106:107], v[158:159]
	s_nop 0
	v_cvt_pk_bf16_f32 v132, v106, v107
	v_mul_f32_e32 v154, 0xbfb8aa3b, v108
	v_mul_f32_e32 v155, 0xbfb8aa3b, v109
	v_exp_f32_e32 v154, v154
	v_exp_f32_e32 v155, v155
	v_lshlrev_b32_e32 v158, 16, v133
	v_and_b32_e32 v159, 0xffff0000, v133
	v_add_f32_e32 v154, 1.0, v154
	v_add_f32_e32 v155, 1.0, v155
	v_rcp_f32_e32 v154, v154
	v_rcp_f32_e32 v155, v155
	v_pk_add_f32 v[158:159], v[158:159], v[196:197] op_sel:[0,1] neg_lo:[0,1] neg_hi:[0,1]
	s_nop 0
	v_pk_mul_f32 v[158:159], v[158:159], v[196:197] op_sel_hi:[1,0]
	v_pk_mul_f32 v[108:109], v[108:109], v[154:155]
	s_nop 0
	v_pk_mul_f32 v[108:109], v[108:109], v[158:159]
	s_nop 0
	v_cvt_pk_bf16_f32 v133, v108, v109
	v_mul_f32_e32 v154, 0xbfb8aa3b, v102
	v_mul_f32_e32 v155, 0xbfb8aa3b, v103
	v_exp_f32_e32 v154, v154
	v_exp_f32_e32 v155, v155
	v_lshlrev_b32_e32 v158, 16, v150
	v_and_b32_e32 v159, 0xffff0000, v150
	v_add_f32_e32 v154, 1.0, v154
	v_add_f32_e32 v155, 1.0, v155
	v_rcp_f32_e32 v154, v154
	v_rcp_f32_e32 v155, v155
	v_pk_add_f32 v[158:159], v[158:159], v[196:197] op_sel:[0,1] neg_lo:[0,1] neg_hi:[0,1]
	s_nop 0
	v_pk_mul_f32 v[158:159], v[158:159], v[196:197] op_sel_hi:[1,0]
	v_pk_mul_f32 v[102:103], v[102:103], v[154:155]
	s_nop 0
	v_pk_mul_f32 v[102:103], v[102:103], v[158:159]
	s_nop 0
	v_cvt_pk_bf16_f32 v150, v102, v103
	v_mul_f32_e32 v154, 0xbfb8aa3b, v104
	v_mul_f32_e32 v155, 0xbfb8aa3b, v105
	v_exp_f32_e32 v154, v154
	v_exp_f32_e32 v155, v155
	v_lshlrev_b32_e32 v158, 16, v151
	v_and_b32_e32 v159, 0xffff0000, v151
	v_add_f32_e32 v154, 1.0, v154
	v_add_f32_e32 v155, 1.0, v155
	v_rcp_f32_e32 v154, v154
	v_rcp_f32_e32 v155, v155
	v_pk_add_f32 v[158:159], v[158:159], v[196:197] op_sel:[0,1] neg_lo:[0,1] neg_hi:[0,1]
	s_nop 0
	v_pk_mul_f32 v[158:159], v[158:159], v[196:197] op_sel_hi:[1,0]
	v_pk_mul_f32 v[104:105], v[104:105], v[154:155]
	s_nop 0
	v_pk_mul_f32 v[104:105], v[104:105], v[158:159]
	s_nop 0
	v_cvt_pk_bf16_f32 v151, v104, v105
	v_mul_f32_e32 v154, 0xbfb8aa3b, v98
	v_mul_f32_e32 v155, 0xbfb8aa3b, v99
	v_exp_f32_e32 v154, v154
	v_exp_f32_e32 v155, v155
	v_lshlrev_b32_e32 v158, 16, v152
	v_and_b32_e32 v159, 0xffff0000, v152
	v_add_f32_e32 v154, 1.0, v154
	v_add_f32_e32 v155, 1.0, v155
	v_rcp_f32_e32 v154, v154
	v_rcp_f32_e32 v155, v155
	v_pk_add_f32 v[158:159], v[158:159], v[196:197] op_sel:[0,1] neg_lo:[0,1] neg_hi:[0,1]
	s_nop 0
	v_pk_mul_f32 v[158:159], v[158:159], v[196:197] op_sel_hi:[1,0]
	v_pk_mul_f32 v[98:99], v[98:99], v[154:155]
	s_nop 0
	v_pk_mul_f32 v[98:99], v[98:99], v[158:159]
	s_nop 0
	v_cvt_pk_bf16_f32 v152, v98, v99
	v_mul_f32_e32 v154, 0xbfb8aa3b, v100
	v_mul_f32_e32 v155, 0xbfb8aa3b, v101
	v_exp_f32_e32 v154, v154
	v_exp_f32_e32 v155, v155
	v_lshlrev_b32_e32 v158, 16, v153
	v_and_b32_e32 v159, 0xffff0000, v153
	v_add_f32_e32 v154, 1.0, v154
	v_add_f32_e32 v155, 1.0, v155
	v_rcp_f32_e32 v154, v154
	v_rcp_f32_e32 v155, v155
	v_pk_add_f32 v[158:159], v[158:159], v[196:197] op_sel:[0,1] neg_lo:[0,1] neg_hi:[0,1]
	s_nop 0
	v_pk_mul_f32 v[158:159], v[158:159], v[196:197] op_sel_hi:[1,0]
	v_pk_mul_f32 v[100:101], v[100:101], v[154:155]
	s_nop 0
	v_pk_mul_f32 v[100:101], v[100:101], v[158:159]
	s_nop 0
	v_cvt_pk_bf16_f32 v153, v100, v101
	s_mul_i32 s83, s82, 1
	v_add_u32_e32 v154, s83, v156
	global_store_dwordx4 v154, v[130:133], s[58:59]
	global_store_dwordx4 v154, v[150:153], s[58:59] offset:256
	s_mul_i32 s83, s82, 11
	v_add_u32_e32 v154, s83, v156
	global_load_dwordx4 v[130:133], v154, s[58:59]
	global_load_dwordx4 v[150:153], v154, s[58:59] offset:256
	s_waitcnt vmcnt(14)
	v_mul_f32_e32 v154, 0xbfb8aa3b, v94
	v_mul_f32_e32 v155, 0xbfb8aa3b, v95
	v_exp_f32_e32 v154, v154
	v_exp_f32_e32 v155, v155
	v_lshlrev_b32_e32 v158, 16, v210
	v_and_b32_e32 v159, 0xffff0000, v210
	v_add_f32_e32 v154, 1.0, v154
	v_add_f32_e32 v155, 1.0, v155
	v_rcp_f32_e32 v154, v154
	v_rcp_f32_e32 v155, v155
	v_pk_add_f32 v[158:159], v[158:159], v[198:199] op_sel:[0,1] neg_lo:[0,1] neg_hi:[0,1]
	s_nop 0
	v_pk_mul_f32 v[158:159], v[158:159], v[198:199] op_sel_hi:[1,0]
	v_pk_mul_f32 v[94:95], v[94:95], v[154:155]
	s_nop 0
	v_pk_mul_f32 v[94:95], v[94:95], v[158:159]
	s_nop 0
	v_cvt_pk_bf16_f32 v210, v94, v95
	v_mul_f32_e32 v154, 0xbfb8aa3b, v96
	v_mul_f32_e32 v155, 0xbfb8aa3b, v97
	v_exp_f32_e32 v154, v154
	v_exp_f32_e32 v155, v155
	v_lshlrev_b32_e32 v158, 16, v211
	v_and_b32_e32 v159, 0xffff0000, v211
	v_add_f32_e32 v154, 1.0, v154
	v_add_f32_e32 v155, 1.0, v155
	v_rcp_f32_e32 v154, v154
	v_rcp_f32_e32 v155, v155
	v_pk_add_f32 v[158:159], v[158:159], v[198:199] op_sel:[0,1] neg_lo:[0,1] neg_hi:[0,1]
	s_nop 0
	v_pk_mul_f32 v[158:159], v[158:159], v[198:199] op_sel_hi:[1,0]
	v_pk_mul_f32 v[96:97], v[96:97], v[154:155]
	s_nop 0
	v_pk_mul_f32 v[96:97], v[96:97], v[158:159]
	s_nop 0
	v_cvt_pk_bf16_f32 v211, v96, v97
	v_mul_f32_e32 v154, 0xbfb8aa3b, v90
	v_mul_f32_e32 v155, 0xbfb8aa3b, v91
	v_exp_f32_e32 v154, v154
	v_exp_f32_e32 v155, v155
	v_lshlrev_b32_e32 v158, 16, v212
	v_and_b32_e32 v159, 0xffff0000, v212
	v_add_f32_e32 v154, 1.0, v154
	v_add_f32_e32 v155, 1.0, v155
	v_rcp_f32_e32 v154, v154
	v_rcp_f32_e32 v155, v155
	v_pk_add_f32 v[158:159], v[158:159], v[198:199] op_sel:[0,1] neg_lo:[0,1] neg_hi:[0,1]
	s_nop 0
	v_pk_mul_f32 v[158:159], v[158:159], v[198:199] op_sel_hi:[1,0]
	v_pk_mul_f32 v[90:91], v[90:91], v[154:155]
	s_nop 0
	v_pk_mul_f32 v[90:91], v[90:91], v[158:159]
	s_nop 0
	v_cvt_pk_bf16_f32 v212, v90, v91
	v_mul_f32_e32 v154, 0xbfb8aa3b, v92
	v_mul_f32_e32 v155, 0xbfb8aa3b, v93
	v_exp_f32_e32 v154, v154
	v_exp_f32_e32 v155, v155
	v_lshlrev_b32_e32 v158, 16, v213
	v_and_b32_e32 v159, 0xffff0000, v213
	v_add_f32_e32 v154, 1.0, v154
	v_add_f32_e32 v155, 1.0, v155
	v_rcp_f32_e32 v154, v154
	v_rcp_f32_e32 v155, v155
	v_pk_add_f32 v[158:159], v[158:159], v[198:199] op_sel:[0,1] neg_lo:[0,1] neg_hi:[0,1]
	s_nop 0
	v_pk_mul_f32 v[158:159], v[158:159], v[198:199] op_sel_hi:[1,0]
	v_pk_mul_f32 v[92:93], v[92:93], v[154:155]
	s_nop 0
	v_pk_mul_f32 v[92:93], v[92:93], v[158:159]
	s_nop 0
	v_cvt_pk_bf16_f32 v213, v92, v93
	v_mul_f32_e32 v154, 0xbfb8aa3b, v86
	v_mul_f32_e32 v155, 0xbfb8aa3b, v87
	v_exp_f32_e32 v154, v154
	v_exp_f32_e32 v155, v155
	v_lshlrev_b32_e32 v158, 16, v214
	v_and_b32_e32 v159, 0xffff0000, v214
	v_add_f32_e32 v154, 1.0, v154
	v_add_f32_e32 v155, 1.0, v155
	v_rcp_f32_e32 v154, v154
	v_rcp_f32_e32 v155, v155
	v_pk_add_f32 v[158:159], v[158:159], v[198:199] op_sel:[0,1] neg_lo:[0,1] neg_hi:[0,1]
	s_nop 0
	v_pk_mul_f32 v[158:159], v[158:159], v[198:199] op_sel_hi:[1,0]
	v_pk_mul_f32 v[86:87], v[86:87], v[154:155]
	s_nop 0
	v_pk_mul_f32 v[86:87], v[86:87], v[158:159]
	s_nop 0
	v_cvt_pk_bf16_f32 v214, v86, v87
	v_mul_f32_e32 v154, 0xbfb8aa3b, v88
	v_mul_f32_e32 v155, 0xbfb8aa3b, v89
	v_exp_f32_e32 v154, v154
	v_exp_f32_e32 v155, v155
	v_lshlrev_b32_e32 v158, 16, v215
	v_and_b32_e32 v159, 0xffff0000, v215
	v_add_f32_e32 v154, 1.0, v154
	v_add_f32_e32 v155, 1.0, v155
	v_rcp_f32_e32 v154, v154
	v_rcp_f32_e32 v155, v155
	v_pk_add_f32 v[158:159], v[158:159], v[198:199] op_sel:[0,1] neg_lo:[0,1] neg_hi:[0,1]
	s_nop 0
	v_pk_mul_f32 v[158:159], v[158:159], v[198:199] op_sel_hi:[1,0]
	v_pk_mul_f32 v[88:89], v[88:89], v[154:155]
	s_nop 0
	v_pk_mul_f32 v[88:89], v[88:89], v[158:159]
	s_nop 0
	v_cvt_pk_bf16_f32 v215, v88, v89
	v_mul_f32_e32 v154, 0xbfb8aa3b, v82
	v_mul_f32_e32 v155, 0xbfb8aa3b, v83
	v_exp_f32_e32 v154, v154
	v_exp_f32_e32 v155, v155
	v_lshlrev_b32_e32 v158, 16, v216
	v_and_b32_e32 v159, 0xffff0000, v216
	v_add_f32_e32 v154, 1.0, v154
	v_add_f32_e32 v155, 1.0, v155
	v_rcp_f32_e32 v154, v154
	v_rcp_f32_e32 v155, v155
	v_pk_add_f32 v[158:159], v[158:159], v[198:199] op_sel:[0,1] neg_lo:[0,1] neg_hi:[0,1]
	s_nop 0
	v_pk_mul_f32 v[158:159], v[158:159], v[198:199] op_sel_hi:[1,0]
	v_pk_mul_f32 v[82:83], v[82:83], v[154:155]
	s_nop 0
	v_pk_mul_f32 v[82:83], v[82:83], v[158:159]
	s_nop 0
	v_cvt_pk_bf16_f32 v216, v82, v83
	v_mul_f32_e32 v154, 0xbfb8aa3b, v84
	v_mul_f32_e32 v155, 0xbfb8aa3b, v85
	v_exp_f32_e32 v154, v154
	v_exp_f32_e32 v155, v155
	v_lshlrev_b32_e32 v158, 16, v217
	v_and_b32_e32 v159, 0xffff0000, v217
	v_add_f32_e32 v154, 1.0, v154
	v_add_f32_e32 v155, 1.0, v155
	v_rcp_f32_e32 v154, v154
	v_rcp_f32_e32 v155, v155
	v_pk_add_f32 v[158:159], v[158:159], v[198:199] op_sel:[0,1] neg_lo:[0,1] neg_hi:[0,1]
	s_nop 0
	v_pk_mul_f32 v[158:159], v[158:159], v[198:199] op_sel_hi:[1,0]
	v_pk_mul_f32 v[84:85], v[84:85], v[154:155]
	s_nop 0
	v_pk_mul_f32 v[84:85], v[84:85], v[158:159]
	s_nop 0
	v_cvt_pk_bf16_f32 v217, v84, v85
	s_mul_i32 s83, s82, 2
	v_add_u32_e32 v154, s83, v156
	global_store_dwordx4 v154, v[210:213], s[58:59]
	global_store_dwordx4 v154, v[214:217], s[58:59] offset:256
	s_waitcnt vmcnt(14)
	v_mul_f32_e32 v154, 0xbfb8aa3b, v78
	v_mul_f32_e32 v155, 0xbfb8aa3b, v79
	v_exp_f32_e32 v154, v154
	v_exp_f32_e32 v155, v155
	v_lshlrev_b32_e32 v158, 16, v218
	v_and_b32_e32 v159, 0xffff0000, v218
	v_add_f32_e32 v154, 1.0, v154
	v_add_f32_e32 v155, 1.0, v155
	v_rcp_f32_e32 v154, v154
	v_rcp_f32_e32 v155, v155
	v_pk_add_f32 v[158:159], v[158:159], v[200:201] op_sel:[0,1] neg_lo:[0,1] neg_hi:[0,1]
	s_nop 0
	v_pk_mul_f32 v[158:159], v[158:159], v[200:201] op_sel_hi:[1,0]
	v_pk_mul_f32 v[78:79], v[78:79], v[154:155]
	s_nop 0
	v_pk_mul_f32 v[78:79], v[78:79], v[158:159]
	s_nop 0
	v_cvt_pk_bf16_f32 v218, v78, v79
	v_mul_f32_e32 v154, 0xbfb8aa3b, v80
	v_mul_f32_e32 v155, 0xbfb8aa3b, v81
	v_exp_f32_e32 v154, v154
	v_exp_f32_e32 v155, v155
	v_lshlrev_b32_e32 v158, 16, v219
	v_and_b32_e32 v159, 0xffff0000, v219
	v_add_f32_e32 v154, 1.0, v154
	v_add_f32_e32 v155, 1.0, v155
	v_rcp_f32_e32 v154, v154
	v_rcp_f32_e32 v155, v155
	v_pk_add_f32 v[158:159], v[158:159], v[200:201] op_sel:[0,1] neg_lo:[0,1] neg_hi:[0,1]
	s_nop 0
	v_pk_mul_f32 v[158:159], v[158:159], v[200:201] op_sel_hi:[1,0]
	v_pk_mul_f32 v[80:81], v[80:81], v[154:155]
	s_nop 0
	v_pk_mul_f32 v[80:81], v[80:81], v[158:159]
	s_nop 0
	v_cvt_pk_bf16_f32 v219, v80, v81
	v_mul_f32_e32 v154, 0xbfb8aa3b, v74
	v_mul_f32_e32 v155, 0xbfb8aa3b, v75
	v_exp_f32_e32 v154, v154
	v_exp_f32_e32 v155, v155
	v_lshlrev_b32_e32 v158, 16, v220
	v_and_b32_e32 v159, 0xffff0000, v220
	v_add_f32_e32 v154, 1.0, v154
	v_add_f32_e32 v155, 1.0, v155
	v_rcp_f32_e32 v154, v154
	v_rcp_f32_e32 v155, v155
	v_pk_add_f32 v[158:159], v[158:159], v[200:201] op_sel:[0,1] neg_lo:[0,1] neg_hi:[0,1]
	s_nop 0
	v_pk_mul_f32 v[158:159], v[158:159], v[200:201] op_sel_hi:[1,0]
	v_pk_mul_f32 v[74:75], v[74:75], v[154:155]
	s_nop 0
	v_pk_mul_f32 v[74:75], v[74:75], v[158:159]
	s_nop 0
	v_cvt_pk_bf16_f32 v220, v74, v75
	v_mul_f32_e32 v154, 0xbfb8aa3b, v76
	v_mul_f32_e32 v155, 0xbfb8aa3b, v77
	v_exp_f32_e32 v154, v154
	v_exp_f32_e32 v155, v155
	v_lshlrev_b32_e32 v158, 16, v221
	v_and_b32_e32 v159, 0xffff0000, v221
	v_add_f32_e32 v154, 1.0, v154
	v_add_f32_e32 v155, 1.0, v155
	v_rcp_f32_e32 v154, v154
	v_rcp_f32_e32 v155, v155
	v_pk_add_f32 v[158:159], v[158:159], v[200:201] op_sel:[0,1] neg_lo:[0,1] neg_hi:[0,1]
	s_nop 0
	v_pk_mul_f32 v[158:159], v[158:159], v[200:201] op_sel_hi:[1,0]
	v_pk_mul_f32 v[76:77], v[76:77], v[154:155]
	s_nop 0
	v_pk_mul_f32 v[76:77], v[76:77], v[158:159]
	s_nop 0
	v_cvt_pk_bf16_f32 v221, v76, v77
	v_mul_f32_e32 v154, 0xbfb8aa3b, v70
	v_mul_f32_e32 v155, 0xbfb8aa3b, v71
	v_exp_f32_e32 v154, v154
	v_exp_f32_e32 v155, v155
	v_lshlrev_b32_e32 v158, 16, v222
	v_and_b32_e32 v159, 0xffff0000, v222
	v_add_f32_e32 v154, 1.0, v154
	v_add_f32_e32 v155, 1.0, v155
	v_rcp_f32_e32 v154, v154
	v_rcp_f32_e32 v155, v155
	v_pk_add_f32 v[158:159], v[158:159], v[200:201] op_sel:[0,1] neg_lo:[0,1] neg_hi:[0,1]
	s_nop 0
	v_pk_mul_f32 v[158:159], v[158:159], v[200:201] op_sel_hi:[1,0]
	v_pk_mul_f32 v[70:71], v[70:71], v[154:155]
	s_nop 0
	v_pk_mul_f32 v[70:71], v[70:71], v[158:159]
	s_nop 0
	v_cvt_pk_bf16_f32 v222, v70, v71
	v_mul_f32_e32 v154, 0xbfb8aa3b, v72
	v_mul_f32_e32 v155, 0xbfb8aa3b, v73
	v_exp_f32_e32 v154, v154
	v_exp_f32_e32 v155, v155
	v_lshlrev_b32_e32 v158, 16, v223
	v_and_b32_e32 v159, 0xffff0000, v223
	v_add_f32_e32 v154, 1.0, v154
	v_add_f32_e32 v155, 1.0, v155
	v_rcp_f32_e32 v154, v154
	v_rcp_f32_e32 v155, v155
	v_pk_add_f32 v[158:159], v[158:159], v[200:201] op_sel:[0,1] neg_lo:[0,1] neg_hi:[0,1]
	s_nop 0
	v_pk_mul_f32 v[158:159], v[158:159], v[200:201] op_sel_hi:[1,0]
	v_pk_mul_f32 v[72:73], v[72:73], v[154:155]
	s_nop 0
	v_pk_mul_f32 v[72:73], v[72:73], v[158:159]
	s_nop 0
	v_cvt_pk_bf16_f32 v223, v72, v73
	v_mul_f32_e32 v154, 0xbfb8aa3b, v66
	v_mul_f32_e32 v155, 0xbfb8aa3b, v67
	v_exp_f32_e32 v154, v154
	v_exp_f32_e32 v155, v155
	v_lshlrev_b32_e32 v158, 16, v224
	v_and_b32_e32 v159, 0xffff0000, v224
	v_add_f32_e32 v154, 1.0, v154
	v_add_f32_e32 v155, 1.0, v155
	v_rcp_f32_e32 v154, v154
	v_rcp_f32_e32 v155, v155
	v_pk_add_f32 v[158:159], v[158:159], v[200:201] op_sel:[0,1] neg_lo:[0,1] neg_hi:[0,1]
	s_nop 0
	v_pk_mul_f32 v[158:159], v[158:159], v[200:201] op_sel_hi:[1,0]
	v_pk_mul_f32 v[66:67], v[66:67], v[154:155]
	s_nop 0
	v_pk_mul_f32 v[66:67], v[66:67], v[158:159]
	s_nop 0
	v_cvt_pk_bf16_f32 v224, v66, v67
	v_mul_f32_e32 v154, 0xbfb8aa3b, v68
	v_mul_f32_e32 v155, 0xbfb8aa3b, v69
	v_exp_f32_e32 v154, v154
	v_exp_f32_e32 v155, v155
	v_lshlrev_b32_e32 v158, 16, v225
	v_and_b32_e32 v159, 0xffff0000, v225
	v_add_f32_e32 v154, 1.0, v154
	v_add_f32_e32 v155, 1.0, v155
	v_rcp_f32_e32 v154, v154
	v_rcp_f32_e32 v155, v155
	v_pk_add_f32 v[158:159], v[158:159], v[200:201] op_sel:[0,1] neg_lo:[0,1] neg_hi:[0,1]
	s_nop 0
	v_pk_mul_f32 v[158:159], v[158:159], v[200:201] op_sel_hi:[1,0]
	v_pk_mul_f32 v[68:69], v[68:69], v[154:155]
	s_nop 0
	v_pk_mul_f32 v[68:69], v[68:69], v[158:159]
	s_nop 0
	v_cvt_pk_bf16_f32 v225, v68, v69
	s_mul_i32 s83, s82, 3
	v_add_u32_e32 v154, s83, v156
	global_store_dwordx4 v154, v[218:221], s[58:59]
	global_store_dwordx4 v154, v[222:225], s[58:59] offset:256
	s_waitcnt vmcnt(14)
	v_mul_f32_e32 v154, 0xbfb8aa3b, v62
	v_mul_f32_e32 v155, 0xbfb8aa3b, v63
	v_exp_f32_e32 v154, v154
	v_exp_f32_e32 v155, v155
	v_lshlrev_b32_e32 v158, 16, v226
	v_and_b32_e32 v159, 0xffff0000, v226
	v_add_f32_e32 v154, 1.0, v154
	v_add_f32_e32 v155, 1.0, v155
	v_rcp_f32_e32 v154, v154
	v_rcp_f32_e32 v155, v155
	v_pk_add_f32 v[158:159], v[158:159], v[202:203] op_sel:[0,1] neg_lo:[0,1] neg_hi:[0,1]
	s_nop 0
	v_pk_mul_f32 v[158:159], v[158:159], v[202:203] op_sel_hi:[1,0]
	v_pk_mul_f32 v[62:63], v[62:63], v[154:155]
	s_nop 0
	v_pk_mul_f32 v[62:63], v[62:63], v[158:159]
	s_nop 0
	v_cvt_pk_bf16_f32 v226, v62, v63
	v_mul_f32_e32 v154, 0xbfb8aa3b, v64
	v_mul_f32_e32 v155, 0xbfb8aa3b, v65
	v_exp_f32_e32 v154, v154
	v_exp_f32_e32 v155, v155
	v_lshlrev_b32_e32 v158, 16, v227
	v_and_b32_e32 v159, 0xffff0000, v227
	v_add_f32_e32 v154, 1.0, v154
	v_add_f32_e32 v155, 1.0, v155
	v_rcp_f32_e32 v154, v154
	v_rcp_f32_e32 v155, v155
	v_pk_add_f32 v[158:159], v[158:159], v[202:203] op_sel:[0,1] neg_lo:[0,1] neg_hi:[0,1]
	s_nop 0
	v_pk_mul_f32 v[158:159], v[158:159], v[202:203] op_sel_hi:[1,0]
	v_pk_mul_f32 v[64:65], v[64:65], v[154:155]
	s_nop 0
	v_pk_mul_f32 v[64:65], v[64:65], v[158:159]
	s_nop 0
	v_cvt_pk_bf16_f32 v227, v64, v65
	v_mul_f32_e32 v154, 0xbfb8aa3b, v58
	v_mul_f32_e32 v155, 0xbfb8aa3b, v59
	v_exp_f32_e32 v154, v154
	v_exp_f32_e32 v155, v155
	v_lshlrev_b32_e32 v158, 16, v228
	v_and_b32_e32 v159, 0xffff0000, v228
	v_add_f32_e32 v154, 1.0, v154
	v_add_f32_e32 v155, 1.0, v155
	v_rcp_f32_e32 v154, v154
	v_rcp_f32_e32 v155, v155
	v_pk_add_f32 v[158:159], v[158:159], v[202:203] op_sel:[0,1] neg_lo:[0,1] neg_hi:[0,1]
	s_nop 0
	v_pk_mul_f32 v[158:159], v[158:159], v[202:203] op_sel_hi:[1,0]
	v_pk_mul_f32 v[58:59], v[58:59], v[154:155]
	s_nop 0
	v_pk_mul_f32 v[58:59], v[58:59], v[158:159]
	s_nop 0
	v_cvt_pk_bf16_f32 v228, v58, v59
	v_mul_f32_e32 v154, 0xbfb8aa3b, v60
	v_mul_f32_e32 v155, 0xbfb8aa3b, v61
	v_exp_f32_e32 v154, v154
	v_exp_f32_e32 v155, v155
	v_lshlrev_b32_e32 v158, 16, v229
	v_and_b32_e32 v159, 0xffff0000, v229
	v_add_f32_e32 v154, 1.0, v154
	v_add_f32_e32 v155, 1.0, v155
	v_rcp_f32_e32 v154, v154
	v_rcp_f32_e32 v155, v155
	v_pk_add_f32 v[158:159], v[158:159], v[202:203] op_sel:[0,1] neg_lo:[0,1] neg_hi:[0,1]
	s_nop 0
	v_pk_mul_f32 v[158:159], v[158:159], v[202:203] op_sel_hi:[1,0]
	v_pk_mul_f32 v[60:61], v[60:61], v[154:155]
	s_nop 0
	v_pk_mul_f32 v[60:61], v[60:61], v[158:159]
	s_nop 0
	v_cvt_pk_bf16_f32 v229, v60, v61
	v_mul_f32_e32 v154, 0xbfb8aa3b, v54
	v_mul_f32_e32 v155, 0xbfb8aa3b, v55
	v_exp_f32_e32 v154, v154
	v_exp_f32_e32 v155, v155
	v_lshlrev_b32_e32 v158, 16, v230
	v_and_b32_e32 v159, 0xffff0000, v230
	v_add_f32_e32 v154, 1.0, v154
	v_add_f32_e32 v155, 1.0, v155
	v_rcp_f32_e32 v154, v154
	v_rcp_f32_e32 v155, v155
	v_pk_add_f32 v[158:159], v[158:159], v[202:203] op_sel:[0,1] neg_lo:[0,1] neg_hi:[0,1]
	s_nop 0
	v_pk_mul_f32 v[158:159], v[158:159], v[202:203] op_sel_hi:[1,0]
	v_pk_mul_f32 v[54:55], v[54:55], v[154:155]
	s_nop 0
	v_pk_mul_f32 v[54:55], v[54:55], v[158:159]
	s_nop 0
	v_cvt_pk_bf16_f32 v230, v54, v55
	v_mul_f32_e32 v154, 0xbfb8aa3b, v56
	v_mul_f32_e32 v155, 0xbfb8aa3b, v57
	v_exp_f32_e32 v154, v154
	v_exp_f32_e32 v155, v155
	v_lshlrev_b32_e32 v158, 16, v231
	v_and_b32_e32 v159, 0xffff0000, v231
	v_add_f32_e32 v154, 1.0, v154
	v_add_f32_e32 v155, 1.0, v155
	v_rcp_f32_e32 v154, v154
	v_rcp_f32_e32 v155, v155
	v_pk_add_f32 v[158:159], v[158:159], v[202:203] op_sel:[0,1] neg_lo:[0,1] neg_hi:[0,1]
	s_nop 0
	v_pk_mul_f32 v[158:159], v[158:159], v[202:203] op_sel_hi:[1,0]
	v_pk_mul_f32 v[56:57], v[56:57], v[154:155]
	s_nop 0
	v_pk_mul_f32 v[56:57], v[56:57], v[158:159]
	s_nop 0
	v_cvt_pk_bf16_f32 v231, v56, v57
	v_mul_f32_e32 v154, 0xbfb8aa3b, v50
	v_mul_f32_e32 v155, 0xbfb8aa3b, v51
	v_exp_f32_e32 v154, v154
	v_exp_f32_e32 v155, v155
	v_lshlrev_b32_e32 v158, 16, v232
	v_and_b32_e32 v159, 0xffff0000, v232
	v_add_f32_e32 v154, 1.0, v154
	v_add_f32_e32 v155, 1.0, v155
	v_rcp_f32_e32 v154, v154
	v_rcp_f32_e32 v155, v155
	v_pk_add_f32 v[158:159], v[158:159], v[202:203] op_sel:[0,1] neg_lo:[0,1] neg_hi:[0,1]
	s_nop 0
	v_pk_mul_f32 v[158:159], v[158:159], v[202:203] op_sel_hi:[1,0]
	v_pk_mul_f32 v[50:51], v[50:51], v[154:155]
	s_nop 0
	v_pk_mul_f32 v[50:51], v[50:51], v[158:159]
	s_nop 0
	v_cvt_pk_bf16_f32 v232, v50, v51
	v_mul_f32_e32 v154, 0xbfb8aa3b, v52
	v_mul_f32_e32 v155, 0xbfb8aa3b, v53
	v_exp_f32_e32 v154, v154
	v_exp_f32_e32 v155, v155
	v_lshlrev_b32_e32 v158, 16, v233
	v_and_b32_e32 v159, 0xffff0000, v233
	v_add_f32_e32 v154, 1.0, v154
	v_add_f32_e32 v155, 1.0, v155
	v_rcp_f32_e32 v154, v154
	v_rcp_f32_e32 v155, v155
	v_pk_add_f32 v[158:159], v[158:159], v[202:203] op_sel:[0,1] neg_lo:[0,1] neg_hi:[0,1]
	s_nop 0
	v_pk_mul_f32 v[158:159], v[158:159], v[202:203] op_sel_hi:[1,0]
	v_pk_mul_f32 v[52:53], v[52:53], v[154:155]
	s_nop 0
	v_pk_mul_f32 v[52:53], v[52:53], v[158:159]
	s_nop 0
	v_cvt_pk_bf16_f32 v233, v52, v53
	s_mul_i32 s83, s82, 8
	v_add_u32_e32 v154, s83, v156
	global_store_dwordx4 v154, v[226:229], s[58:59]
	global_store_dwordx4 v154, v[230:233], s[58:59] offset:256
	s_waitcnt vmcnt(14)
	v_mul_f32_e32 v154, 0xbfb8aa3b, v46
	v_mul_f32_e32 v155, 0xbfb8aa3b, v47
	v_exp_f32_e32 v154, v154
	v_exp_f32_e32 v155, v155
	v_lshlrev_b32_e32 v158, 16, v234
	v_and_b32_e32 v159, 0xffff0000, v234
	v_add_f32_e32 v154, 1.0, v154
	v_add_f32_e32 v155, 1.0, v155
	v_rcp_f32_e32 v154, v154
	v_rcp_f32_e32 v155, v155
	v_pk_add_f32 v[158:159], v[158:159], v[204:205] op_sel:[0,1] neg_lo:[0,1] neg_hi:[0,1]
	s_nop 0
	v_pk_mul_f32 v[158:159], v[158:159], v[204:205] op_sel_hi:[1,0]
	v_pk_mul_f32 v[46:47], v[46:47], v[154:155]
	s_nop 0
	v_pk_mul_f32 v[46:47], v[46:47], v[158:159]
	s_nop 0
	v_cvt_pk_bf16_f32 v234, v46, v47
	v_mul_f32_e32 v154, 0xbfb8aa3b, v48
	v_mul_f32_e32 v155, 0xbfb8aa3b, v49
	v_exp_f32_e32 v154, v154
	v_exp_f32_e32 v155, v155
	v_lshlrev_b32_e32 v158, 16, v235
	v_and_b32_e32 v159, 0xffff0000, v235
	v_add_f32_e32 v154, 1.0, v154
	v_add_f32_e32 v155, 1.0, v155
	v_rcp_f32_e32 v154, v154
	v_rcp_f32_e32 v155, v155
	v_pk_add_f32 v[158:159], v[158:159], v[204:205] op_sel:[0,1] neg_lo:[0,1] neg_hi:[0,1]
	s_nop 0
	v_pk_mul_f32 v[158:159], v[158:159], v[204:205] op_sel_hi:[1,0]
	v_pk_mul_f32 v[48:49], v[48:49], v[154:155]
	s_nop 0
	v_pk_mul_f32 v[48:49], v[48:49], v[158:159]
	s_nop 0
	v_cvt_pk_bf16_f32 v235, v48, v49
	v_mul_f32_e32 v154, 0xbfb8aa3b, v42
	v_mul_f32_e32 v155, 0xbfb8aa3b, v43
	v_exp_f32_e32 v154, v154
	v_exp_f32_e32 v155, v155
	v_lshlrev_b32_e32 v158, 16, v236
	v_and_b32_e32 v159, 0xffff0000, v236
	v_add_f32_e32 v154, 1.0, v154
	v_add_f32_e32 v155, 1.0, v155
	v_rcp_f32_e32 v154, v154
	v_rcp_f32_e32 v155, v155
	v_pk_add_f32 v[158:159], v[158:159], v[204:205] op_sel:[0,1] neg_lo:[0,1] neg_hi:[0,1]
	s_nop 0
	v_pk_mul_f32 v[158:159], v[158:159], v[204:205] op_sel_hi:[1,0]
	v_pk_mul_f32 v[42:43], v[42:43], v[154:155]
	s_nop 0
	v_pk_mul_f32 v[42:43], v[42:43], v[158:159]
	s_nop 0
	v_cvt_pk_bf16_f32 v236, v42, v43
	v_mul_f32_e32 v154, 0xbfb8aa3b, v44
	v_mul_f32_e32 v155, 0xbfb8aa3b, v45
	v_exp_f32_e32 v154, v154
	v_exp_f32_e32 v155, v155
	v_lshlrev_b32_e32 v158, 16, v237
	v_and_b32_e32 v159, 0xffff0000, v237
	v_add_f32_e32 v154, 1.0, v154
	v_add_f32_e32 v155, 1.0, v155
	v_rcp_f32_e32 v154, v154
	v_rcp_f32_e32 v155, v155
	v_pk_add_f32 v[158:159], v[158:159], v[204:205] op_sel:[0,1] neg_lo:[0,1] neg_hi:[0,1]
	s_nop 0
	v_pk_mul_f32 v[158:159], v[158:159], v[204:205] op_sel_hi:[1,0]
	v_pk_mul_f32 v[44:45], v[44:45], v[154:155]
	s_nop 0
	v_pk_mul_f32 v[44:45], v[44:45], v[158:159]
	s_nop 0
	v_cvt_pk_bf16_f32 v237, v44, v45
	v_mul_f32_e32 v154, 0xbfb8aa3b, v38
	v_mul_f32_e32 v155, 0xbfb8aa3b, v39
	v_exp_f32_e32 v154, v154
	v_exp_f32_e32 v155, v155
	v_lshlrev_b32_e32 v158, 16, v238
	v_and_b32_e32 v159, 0xffff0000, v238
	v_add_f32_e32 v154, 1.0, v154
	v_add_f32_e32 v155, 1.0, v155
	v_rcp_f32_e32 v154, v154
	v_rcp_f32_e32 v155, v155
	v_pk_add_f32 v[158:159], v[158:159], v[204:205] op_sel:[0,1] neg_lo:[0,1] neg_hi:[0,1]
	s_nop 0
	v_pk_mul_f32 v[158:159], v[158:159], v[204:205] op_sel_hi:[1,0]
	v_pk_mul_f32 v[38:39], v[38:39], v[154:155]
	s_nop 0
	v_pk_mul_f32 v[38:39], v[38:39], v[158:159]
	s_nop 0
	v_cvt_pk_bf16_f32 v238, v38, v39
	v_mul_f32_e32 v154, 0xbfb8aa3b, v40
	v_mul_f32_e32 v155, 0xbfb8aa3b, v41
	v_exp_f32_e32 v154, v154
	v_exp_f32_e32 v155, v155
	v_lshlrev_b32_e32 v158, 16, v239
	v_and_b32_e32 v159, 0xffff0000, v239
	v_add_f32_e32 v154, 1.0, v154
	v_add_f32_e32 v155, 1.0, v155
	v_rcp_f32_e32 v154, v154
	v_rcp_f32_e32 v155, v155
	v_pk_add_f32 v[158:159], v[158:159], v[204:205] op_sel:[0,1] neg_lo:[0,1] neg_hi:[0,1]
	s_nop 0
	v_pk_mul_f32 v[158:159], v[158:159], v[204:205] op_sel_hi:[1,0]
	v_pk_mul_f32 v[40:41], v[40:41], v[154:155]
	s_nop 0
	v_pk_mul_f32 v[40:41], v[40:41], v[158:159]
	s_nop 0
	v_cvt_pk_bf16_f32 v239, v40, v41
	v_mul_f32_e32 v154, 0xbfb8aa3b, v34
	v_mul_f32_e32 v155, 0xbfb8aa3b, v35
	v_exp_f32_e32 v154, v154
	v_exp_f32_e32 v155, v155
	v_lshlrev_b32_e32 v158, 16, v240
	v_and_b32_e32 v159, 0xffff0000, v240
	v_add_f32_e32 v154, 1.0, v154
	v_add_f32_e32 v155, 1.0, v155
	v_rcp_f32_e32 v154, v154
	v_rcp_f32_e32 v155, v155
	v_pk_add_f32 v[158:159], v[158:159], v[204:205] op_sel:[0,1] neg_lo:[0,1] neg_hi:[0,1]
	s_nop 0
	v_pk_mul_f32 v[158:159], v[158:159], v[204:205] op_sel_hi:[1,0]
	v_pk_mul_f32 v[34:35], v[34:35], v[154:155]
	s_nop 0
	v_pk_mul_f32 v[34:35], v[34:35], v[158:159]
	s_nop 0
	v_cvt_pk_bf16_f32 v240, v34, v35
	v_mul_f32_e32 v154, 0xbfb8aa3b, v36
	v_mul_f32_e32 v155, 0xbfb8aa3b, v37
	v_exp_f32_e32 v154, v154
	v_exp_f32_e32 v155, v155
	v_lshlrev_b32_e32 v158, 16, v241
	v_and_b32_e32 v159, 0xffff0000, v241
	v_add_f32_e32 v154, 1.0, v154
	v_add_f32_e32 v155, 1.0, v155
	v_rcp_f32_e32 v154, v154
	v_rcp_f32_e32 v155, v155
	v_pk_add_f32 v[158:159], v[158:159], v[204:205] op_sel:[0,1] neg_lo:[0,1] neg_hi:[0,1]
	s_nop 0
	v_pk_mul_f32 v[158:159], v[158:159], v[204:205] op_sel_hi:[1,0]
	v_pk_mul_f32 v[36:37], v[36:37], v[154:155]
	s_nop 0
	v_pk_mul_f32 v[36:37], v[36:37], v[158:159]
	s_nop 0
	v_cvt_pk_bf16_f32 v241, v36, v37
	s_mul_i32 s83, s82, 9
	v_add_u32_e32 v154, s83, v156
	global_store_dwordx4 v154, v[234:237], s[58:59]
	global_store_dwordx4 v154, v[238:241], s[58:59] offset:256
	s_waitcnt vmcnt(12)
	v_mul_f32_e32 v154, 0xbfb8aa3b, v28
	v_mul_f32_e32 v155, 0xbfb8aa3b, v29
	v_exp_f32_e32 v154, v154
	v_exp_f32_e32 v155, v155
	v_lshlrev_b32_e32 v158, 16, v162
	v_and_b32_e32 v159, 0xffff0000, v162
	v_add_f32_e32 v154, 1.0, v154
	v_add_f32_e32 v155, 1.0, v155
	v_rcp_f32_e32 v154, v154
	v_rcp_f32_e32 v155, v155
	v_pk_add_f32 v[158:159], v[158:159], v[206:207] op_sel:[0,1] neg_lo:[0,1] neg_hi:[0,1]
	s_nop 0
	v_pk_mul_f32 v[158:159], v[158:159], v[206:207] op_sel_hi:[1,0]
	v_pk_mul_f32 v[28:29], v[28:29], v[154:155]
	s_nop 0
	v_pk_mul_f32 v[28:29], v[28:29], v[158:159]
	s_nop 0
	v_cvt_pk_bf16_f32 v162, v28, v29
	v_mul_f32_e32 v154, 0xbfb8aa3b, v30
	v_mul_f32_e32 v155, 0xbfb8aa3b, v31
	v_exp_f32_e32 v154, v154
	v_exp_f32_e32 v155, v155
	v_lshlrev_b32_e32 v158, 16, v163
	v_and_b32_e32 v159, 0xffff0000, v163
	v_add_f32_e32 v154, 1.0, v154
	v_add_f32_e32 v155, 1.0, v155
	v_rcp_f32_e32 v154, v154
	v_rcp_f32_e32 v155, v155
	v_pk_add_f32 v[158:159], v[158:159], v[206:207] op_sel:[0,1] neg_lo:[0,1] neg_hi:[0,1]
	s_nop 0
	v_pk_mul_f32 v[158:159], v[158:159], v[206:207] op_sel_hi:[1,0]
	v_pk_mul_f32 v[30:31], v[30:31], v[154:155]
	s_nop 0
	v_pk_mul_f32 v[30:31], v[30:31], v[158:159]
	s_nop 0
	v_cvt_pk_bf16_f32 v163, v30, v31
	v_mul_f32_e32 v154, 0xbfb8aa3b, v24
	v_mul_f32_e32 v155, 0xbfb8aa3b, v25
	v_exp_f32_e32 v154, v154
	v_exp_f32_e32 v155, v155
	v_lshlrev_b32_e32 v158, 16, v164
	v_and_b32_e32 v159, 0xffff0000, v164
	v_add_f32_e32 v154, 1.0, v154
	v_add_f32_e32 v155, 1.0, v155
	v_rcp_f32_e32 v154, v154
	v_rcp_f32_e32 v155, v155
	v_pk_add_f32 v[158:159], v[158:159], v[206:207] op_sel:[0,1] neg_lo:[0,1] neg_hi:[0,1]
	s_nop 0
	v_pk_mul_f32 v[158:159], v[158:159], v[206:207] op_sel_hi:[1,0]
	v_pk_mul_f32 v[24:25], v[24:25], v[154:155]
	s_nop 0
	v_pk_mul_f32 v[24:25], v[24:25], v[158:159]
	s_nop 0
	v_cvt_pk_bf16_f32 v164, v24, v25
	v_mul_f32_e32 v154, 0xbfb8aa3b, v26
	v_mul_f32_e32 v155, 0xbfb8aa3b, v27
	v_exp_f32_e32 v154, v154
	v_exp_f32_e32 v155, v155
	v_lshlrev_b32_e32 v158, 16, v165
	v_and_b32_e32 v159, 0xffff0000, v165
	v_add_f32_e32 v154, 1.0, v154
	v_add_f32_e32 v155, 1.0, v155
	v_rcp_f32_e32 v154, v154
	v_rcp_f32_e32 v155, v155
	v_pk_add_f32 v[158:159], v[158:159], v[206:207] op_sel:[0,1] neg_lo:[0,1] neg_hi:[0,1]
	s_nop 0
	v_pk_mul_f32 v[158:159], v[158:159], v[206:207] op_sel_hi:[1,0]
	v_pk_mul_f32 v[26:27], v[26:27], v[154:155]
	s_nop 0
	v_pk_mul_f32 v[26:27], v[26:27], v[158:159]
	s_nop 0
	v_cvt_pk_bf16_f32 v165, v26, v27
	v_mul_f32_e32 v154, 0xbfb8aa3b, v20
	v_mul_f32_e32 v155, 0xbfb8aa3b, v21
	v_exp_f32_e32 v154, v154
	v_exp_f32_e32 v155, v155
	v_lshlrev_b32_e32 v158, 16, v166
	v_and_b32_e32 v159, 0xffff0000, v166
	v_add_f32_e32 v154, 1.0, v154
	v_add_f32_e32 v155, 1.0, v155
	v_rcp_f32_e32 v154, v154
	v_rcp_f32_e32 v155, v155
	v_pk_add_f32 v[158:159], v[158:159], v[206:207] op_sel:[0,1] neg_lo:[0,1] neg_hi:[0,1]
	s_nop 0
	v_pk_mul_f32 v[158:159], v[158:159], v[206:207] op_sel_hi:[1,0]
	v_pk_mul_f32 v[20:21], v[20:21], v[154:155]
	s_nop 0
	v_pk_mul_f32 v[20:21], v[20:21], v[158:159]
	s_nop 0
	v_cvt_pk_bf16_f32 v166, v20, v21
	v_mul_f32_e32 v154, 0xbfb8aa3b, v22
	v_mul_f32_e32 v155, 0xbfb8aa3b, v23
	v_exp_f32_e32 v154, v154
	v_exp_f32_e32 v155, v155
	v_lshlrev_b32_e32 v158, 16, v167
	v_and_b32_e32 v159, 0xffff0000, v167
	v_add_f32_e32 v154, 1.0, v154
	v_add_f32_e32 v155, 1.0, v155
	v_rcp_f32_e32 v154, v154
	v_rcp_f32_e32 v155, v155
	v_pk_add_f32 v[158:159], v[158:159], v[206:207] op_sel:[0,1] neg_lo:[0,1] neg_hi:[0,1]
	s_nop 0
	v_pk_mul_f32 v[158:159], v[158:159], v[206:207] op_sel_hi:[1,0]
	v_pk_mul_f32 v[22:23], v[22:23], v[154:155]
	s_nop 0
	v_pk_mul_f32 v[22:23], v[22:23], v[158:159]
	s_nop 0
	v_cvt_pk_bf16_f32 v167, v22, v23
	v_mul_f32_e32 v154, 0xbfb8aa3b, v16
	v_mul_f32_e32 v155, 0xbfb8aa3b, v17
	v_exp_f32_e32 v154, v154
	v_exp_f32_e32 v155, v155
	v_lshlrev_b32_e32 v158, 16, v168
	v_and_b32_e32 v159, 0xffff0000, v168
	v_add_f32_e32 v154, 1.0, v154
	v_add_f32_e32 v155, 1.0, v155
	v_rcp_f32_e32 v154, v154
	v_rcp_f32_e32 v155, v155
	v_pk_add_f32 v[158:159], v[158:159], v[206:207] op_sel:[0,1] neg_lo:[0,1] neg_hi:[0,1]
	s_nop 0
	v_pk_mul_f32 v[158:159], v[158:159], v[206:207] op_sel_hi:[1,0]
	v_pk_mul_f32 v[16:17], v[16:17], v[154:155]
	s_nop 0
	v_pk_mul_f32 v[16:17], v[16:17], v[158:159]
	s_nop 0
	v_cvt_pk_bf16_f32 v168, v16, v17
	v_mul_f32_e32 v154, 0xbfb8aa3b, v18
	v_mul_f32_e32 v155, 0xbfb8aa3b, v19
	v_exp_f32_e32 v154, v154
	v_exp_f32_e32 v155, v155
	v_lshlrev_b32_e32 v158, 16, v169
	v_and_b32_e32 v159, 0xffff0000, v169
	v_add_f32_e32 v154, 1.0, v154
	v_add_f32_e32 v155, 1.0, v155
	v_rcp_f32_e32 v154, v154
	v_rcp_f32_e32 v155, v155
	v_pk_add_f32 v[158:159], v[158:159], v[206:207] op_sel:[0,1] neg_lo:[0,1] neg_hi:[0,1]
	s_nop 0
	v_pk_mul_f32 v[158:159], v[158:159], v[206:207] op_sel_hi:[1,0]
	v_pk_mul_f32 v[18:19], v[18:19], v[154:155]
	s_nop 0
	v_pk_mul_f32 v[18:19], v[18:19], v[158:159]
	s_nop 0
	v_cvt_pk_bf16_f32 v169, v18, v19
	s_mul_i32 s83, s82, 10
	v_add_u32_e32 v154, s83, v156
	global_store_dwordx4 v154, v[162:165], s[58:59]
	global_store_dwordx4 v154, v[166:169], s[58:59] offset:256
	s_waitcnt vmcnt(10)
	v_mul_f32_e32 v154, 0xbfb8aa3b, v12
	v_mul_f32_e32 v155, 0xbfb8aa3b, v13
	v_exp_f32_e32 v154, v154
	v_exp_f32_e32 v155, v155
	v_lshlrev_b32_e32 v158, 16, v130
	v_and_b32_e32 v159, 0xffff0000, v130
	v_add_f32_e32 v154, 1.0, v154
	v_add_f32_e32 v155, 1.0, v155
	v_rcp_f32_e32 v154, v154
	v_rcp_f32_e32 v155, v155
	v_pk_add_f32 v[158:159], v[158:159], v[208:209] op_sel:[0,1] neg_lo:[0,1] neg_hi:[0,1]
	s_nop 0
	v_pk_mul_f32 v[158:159], v[158:159], v[208:209] op_sel_hi:[1,0]
	v_pk_mul_f32 v[12:13], v[12:13], v[154:155]
	s_nop 0
	v_pk_mul_f32 v[12:13], v[12:13], v[158:159]
	s_nop 0
	v_cvt_pk_bf16_f32 v130, v12, v13
	v_mul_f32_e32 v154, 0xbfb8aa3b, v14
	v_mul_f32_e32 v155, 0xbfb8aa3b, v15
	v_exp_f32_e32 v154, v154
	v_exp_f32_e32 v155, v155
	v_lshlrev_b32_e32 v158, 16, v131
	v_and_b32_e32 v159, 0xffff0000, v131
	v_add_f32_e32 v154, 1.0, v154
	v_add_f32_e32 v155, 1.0, v155
	v_rcp_f32_e32 v154, v154
	v_rcp_f32_e32 v155, v155
	v_pk_add_f32 v[158:159], v[158:159], v[208:209] op_sel:[0,1] neg_lo:[0,1] neg_hi:[0,1]
	s_nop 0
	v_pk_mul_f32 v[158:159], v[158:159], v[208:209] op_sel_hi:[1,0]
	v_pk_mul_f32 v[14:15], v[14:15], v[154:155]
	s_nop 0
	v_pk_mul_f32 v[14:15], v[14:15], v[158:159]
	s_nop 0
	v_cvt_pk_bf16_f32 v131, v14, v15
	v_mul_f32_e32 v154, 0xbfb8aa3b, v8
	v_mul_f32_e32 v155, 0xbfb8aa3b, v9
	v_exp_f32_e32 v154, v154
	v_exp_f32_e32 v155, v155
	v_lshlrev_b32_e32 v158, 16, v132
	v_and_b32_e32 v159, 0xffff0000, v132
	v_add_f32_e32 v154, 1.0, v154
	v_add_f32_e32 v155, 1.0, v155
	v_rcp_f32_e32 v154, v154
	v_rcp_f32_e32 v155, v155
	v_pk_add_f32 v[158:159], v[158:159], v[208:209] op_sel:[0,1] neg_lo:[0,1] neg_hi:[0,1]
	s_nop 0
	v_pk_mul_f32 v[158:159], v[158:159], v[208:209] op_sel_hi:[1,0]
	v_pk_mul_f32 v[8:9], v[8:9], v[154:155]
	s_nop 0
	v_pk_mul_f32 v[8:9], v[8:9], v[158:159]
	s_nop 0
	v_cvt_pk_bf16_f32 v132, v8, v9
	v_mul_f32_e32 v154, 0xbfb8aa3b, v10
	v_mul_f32_e32 v155, 0xbfb8aa3b, v11
	v_exp_f32_e32 v154, v154
	v_exp_f32_e32 v155, v155
	v_lshlrev_b32_e32 v158, 16, v133
	v_and_b32_e32 v159, 0xffff0000, v133
	v_add_f32_e32 v154, 1.0, v154
	v_add_f32_e32 v155, 1.0, v155
	v_rcp_f32_e32 v154, v154
	v_rcp_f32_e32 v155, v155
	v_pk_add_f32 v[158:159], v[158:159], v[208:209] op_sel:[0,1] neg_lo:[0,1] neg_hi:[0,1]
	s_nop 0
	v_pk_mul_f32 v[158:159], v[158:159], v[208:209] op_sel_hi:[1,0]
	v_pk_mul_f32 v[10:11], v[10:11], v[154:155]
	s_nop 0
	v_pk_mul_f32 v[10:11], v[10:11], v[158:159]
	s_nop 0
	v_cvt_pk_bf16_f32 v133, v10, v11
	v_mul_f32_e32 v154, 0xbfb8aa3b, v4
	v_mul_f32_e32 v155, 0xbfb8aa3b, v5
	v_exp_f32_e32 v154, v154
	v_exp_f32_e32 v155, v155
	v_lshlrev_b32_e32 v158, 16, v150
	v_and_b32_e32 v159, 0xffff0000, v150
	v_add_f32_e32 v154, 1.0, v154
	v_add_f32_e32 v155, 1.0, v155
	v_rcp_f32_e32 v154, v154
	v_rcp_f32_e32 v155, v155
	v_pk_add_f32 v[158:159], v[158:159], v[208:209] op_sel:[0,1] neg_lo:[0,1] neg_hi:[0,1]
	s_nop 0
	v_pk_mul_f32 v[158:159], v[158:159], v[208:209] op_sel_hi:[1,0]
	v_pk_mul_f32 v[4:5], v[4:5], v[154:155]
	s_nop 0
	v_pk_mul_f32 v[4:5], v[4:5], v[158:159]
	s_nop 0
	v_cvt_pk_bf16_f32 v150, v4, v5
	v_mul_f32_e32 v154, 0xbfb8aa3b, v6
	v_mul_f32_e32 v155, 0xbfb8aa3b, v7
	v_exp_f32_e32 v154, v154
	v_exp_f32_e32 v155, v155
	v_lshlrev_b32_e32 v158, 16, v151
	v_and_b32_e32 v159, 0xffff0000, v151
	v_add_f32_e32 v154, 1.0, v154
	v_add_f32_e32 v155, 1.0, v155
	v_rcp_f32_e32 v154, v154
	v_rcp_f32_e32 v155, v155
	v_pk_add_f32 v[158:159], v[158:159], v[208:209] op_sel:[0,1] neg_lo:[0,1] neg_hi:[0,1]
	s_nop 0
	v_pk_mul_f32 v[158:159], v[158:159], v[208:209] op_sel_hi:[1,0]
	v_pk_mul_f32 v[6:7], v[6:7], v[154:155]
	s_nop 0
	v_pk_mul_f32 v[6:7], v[6:7], v[158:159]
	s_nop 0
	v_cvt_pk_bf16_f32 v151, v6, v7
	v_mul_f32_e32 v154, 0xbfb8aa3b, v0
	v_mul_f32_e32 v155, 0xbfb8aa3b, v1
	v_exp_f32_e32 v154, v154
	v_exp_f32_e32 v155, v155
	v_lshlrev_b32_e32 v158, 16, v152
	v_and_b32_e32 v159, 0xffff0000, v152
	v_add_f32_e32 v154, 1.0, v154
	v_add_f32_e32 v155, 1.0, v155
	v_rcp_f32_e32 v154, v154
	v_rcp_f32_e32 v155, v155
	v_pk_add_f32 v[158:159], v[158:159], v[208:209] op_sel:[0,1] neg_lo:[0,1] neg_hi:[0,1]
	s_nop 0
	v_pk_mul_f32 v[158:159], v[158:159], v[208:209] op_sel_hi:[1,0]
	v_pk_mul_f32 v[0:1], v[0:1], v[154:155]
	s_nop 0
	v_pk_mul_f32 v[0:1], v[0:1], v[158:159]
	s_nop 0
	v_cvt_pk_bf16_f32 v152, v0, v1
	v_mul_f32_e32 v154, 0xbfb8aa3b, v2
	v_mul_f32_e32 v155, 0xbfb8aa3b, v3
	v_exp_f32_e32 v154, v154
	v_exp_f32_e32 v155, v155
	v_lshlrev_b32_e32 v158, 16, v153
	v_and_b32_e32 v159, 0xffff0000, v153
	v_add_f32_e32 v154, 1.0, v154
	v_add_f32_e32 v155, 1.0, v155
	v_rcp_f32_e32 v154, v154
	v_rcp_f32_e32 v155, v155
	v_pk_add_f32 v[158:159], v[158:159], v[208:209] op_sel:[0,1] neg_lo:[0,1] neg_hi:[0,1]
	s_nop 0
	v_pk_mul_f32 v[158:159], v[158:159], v[208:209] op_sel_hi:[1,0]
	v_pk_mul_f32 v[2:3], v[2:3], v[154:155]
	s_nop 0
	v_pk_mul_f32 v[2:3], v[2:3], v[158:159]
	s_nop 0
	v_cvt_pk_bf16_f32 v153, v2, v3
	s_mul_i32 s83, s82, 11
	v_add_u32_e32 v154, s83, v156
	global_store_dwordx4 v154, v[130:133], s[58:59]
	global_store_dwordx4 v154, v[150:153], s[58:59] offset:256
	s_mov_b64 s[82:83], -1
	s_and_b64 vcc, exec, s[42:43]
	s_cbranch_vccnz .LBB0_252
	s_andn2_b64 vcc, exec, s[76:77]
	s_cbranch_vccnz .LBB0_251
	s_barrier
	s_branch .LBB0_251
